# P0: nt cache policy also on the once-read f32 weight loads of the transposes and the mem row loads
# speedup vs baseline: 1.0292x; 1.0088x over previous
; #define LAS __attribute__((address_space(3)))
; __device__ __forceinline__ void tr_item(const float* W, int ldw, int K, int k0, int sc0, bf16* WT, int dr0, const float* gain, float cs, LAS float* scr, int lane) {
; #pragma unroll 16
;     for (int i = 0; i < 32; ++i) { const int kk = 2 * i + (lane >> 5); const float g = gain ? gain[k0 + kk] * cs : cs;
;         scr[kk * 33 + (lane & 31)] = W[(size_t)(k0 + kk) * ldw + sc0 + (lane & 31)] * g; }
; __global__ void __launch_bounds__(NTHR, 2) hybrid_fwd(Args args) {
;     ...
;             { const int kb = r / 32, nb = r % 32; tr_item(w_ffn_out, 1024, DFF, 64 * kb, 32 * nb, Wffo, 32 * nb, nullptr, 1.0f, scr, lane); }
.LBB0_18:
	s_cmpk_gt_i32 s70, 0x7ff
	s_mov_b64 s[4:5], -1
	s_cbranch_scc0 .LBB0_151
	s_cmpk_gt_u32 s70, 0x8ff
	s_cbranch_scc0 .LBB0_148
	s_cmpk_gt_u32 s70, 0xaff
	s_cbranch_scc0 .LBB0_145
	s_lshr_b32 s60, s27, 5
	s_cmpk_gt_u32 s70, 0xbff
	s_cbranch_scc0 .LBB0_108
	s_lshr_b32 s61, s68, 6
	s_cmpk_gt_u32 s70, 0xdff
	s_cbranch_scc0 .LBB0_71
	s_cmpk_gt_u32 s70, 0xeff
	s_cbranch_scc0 .LBB0_68
	s_cmpk_gt_u32 s70, 0x19ff
	s_cbranch_scc0 .LBB0_31
	s_mul_i32 s4, s21, s69
	s_add_i32 s4, s3, s4
	s_and_b32 s4, s4, 0x7fffffc0
	s_lshl_b32 s5, s70, 5
	v_add_u32_e32 v78, s4, v117
	s_lshl_b32 s4, s70, 1
	s_and_b32 s58, s5, 0x3e0
	s_and_b32 s4, s4, 0x7fffffc0
	s_lshl_b32 s44, s58, 2
	s_addk_i32 s4, 0xcc00
	v_lshl_add_u64 v[76:77], v[4:5], 0, s[44:45]
	v_cmp_gt_i32_e32 vcc, s64, v78
	s_and_saveexec_b64 s[56:57], vcc
	s_xor_b64 s[56:57], exec, s[56:57]
	s_cbranch_execz .LBB0_27
	v_add_u32_e32 v80, s4, v2
	v_add_u32_e32 v78, s4, v1
	v_ashrrev_i32_e32 v81, 31, v80
	v_add_u32_e32 v82, s4, v3
	v_add_u32_e32 v84, s4, v46
	v_add_u32_e32 v86, s4, v33
	v_add_u32_e32 v88, s4, v48
	v_add_u32_e32 v90, s4, v47
	v_add_u32_e32 v92, s4, v50
	v_ashrrev_i32_e32 v79, 31, v78
	v_lshlrev_b64 v[80:81], 12, v[80:81]
	v_ashrrev_i32_e32 v85, 31, v84
	v_ashrrev_i32_e32 v83, 31, v82
	v_ashrrev_i32_e32 v89, 31, v88
	v_ashrrev_i32_e32 v87, 31, v86
	v_ashrrev_i32_e32 v93, 31, v92
	v_ashrrev_i32_e32 v91, 31, v90
	v_lshlrev_b64 v[78:79], 12, v[78:79]
	v_lshl_add_u64 v[80:81], v[76:77], 0, v[80:81]
	v_lshlrev_b64 v[82:83], 12, v[82:83]
	v_lshlrev_b64 v[84:85], 12, v[84:85]
	v_lshlrev_b64 v[86:87], 12, v[86:87]
	v_lshlrev_b64 v[88:89], 12, v[88:89]
	v_lshlrev_b64 v[90:91], 12, v[90:91]
	v_lshlrev_b64 v[92:93], 12, v[92:93]
	v_lshl_add_u64 v[78:79], v[76:77], 0, v[78:79]
	v_lshl_add_u64 v[84:85], v[76:77], 0, v[84:85]
	v_lshl_add_u64 v[82:83], v[76:77], 0, v[82:83]
	v_lshl_add_u64 v[88:89], v[76:77], 0, v[88:89]
	v_lshl_add_u64 v[86:87], v[76:77], 0, v[86:87]
	v_lshl_add_u64 v[92:93], v[76:77], 0, v[92:93]
	v_lshl_add_u64 v[90:91], v[76:77], 0, v[90:91]
	global_load_dword v94, v[80:81], off nt
	global_load_dword v95, v[78:79], off nt
	global_load_dword v96, v[84:85], off nt
	global_load_dword v97, v[82:83], off nt
	global_load_dword v98, v[88:89], off nt
	global_load_dword v99, v[86:87], off nt
	global_load_dword v100, v[92:93], off nt
	global_load_dword v101, v[90:91], off nt
	v_add_u32_e32 v80, s4, v52
	v_add_u32_e32 v78, s4, v49
	v_ashrrev_i32_e32 v81, 31, v80
	v_add_u32_e32 v82, s4, v51
	v_add_u32_e32 v84, s4, v54
	v_add_u32_e32 v86, s4, v53
	v_add_u32_e32 v88, s4, v56
	v_add_u32_e32 v90, s4, v55
	v_add_u32_e32 v92, s4, v58
	v_ashrrev_i32_e32 v79, 31, v78
	v_lshlrev_b64 v[80:81], 12, v[80:81]
	v_ashrrev_i32_e32 v85, 31, v84
	v_ashrrev_i32_e32 v83, 31, v82
	v_ashrrev_i32_e32 v89, 31, v88
	v_ashrrev_i32_e32 v87, 31, v86
	v_ashrrev_i32_e32 v93, 31, v92
	v_ashrrev_i32_e32 v91, 31, v90
	v_lshlrev_b64 v[78:79], 12, v[78:79]
	v_lshl_add_u64 v[80:81], v[76:77], 0, v[80:81]
	v_lshlrev_b64 v[82:83], 12, v[82:83]
	v_lshlrev_b64 v[84:85], 12, v[84:85]
	v_lshlrev_b64 v[86:87], 12, v[86:87]
	v_lshlrev_b64 v[88:89], 12, v[88:89]
	v_lshlrev_b64 v[90:91], 12, v[90:91]
	v_lshlrev_b64 v[92:93], 12, v[92:93]
	v_lshl_add_u64 v[78:79], v[76:77], 0, v[78:79]
	v_lshl_add_u64 v[84:85], v[76:77], 0, v[84:85]
	v_lshl_add_u64 v[82:83], v[76:77], 0, v[82:83]
	v_lshl_add_u64 v[88:89], v[76:77], 0, v[88:89]
	v_lshl_add_u64 v[86:87], v[76:77], 0, v[86:87]
	v_lshl_add_u64 v[92:93], v[76:77], 0, v[92:93]
	v_lshl_add_u64 v[90:91], v[76:77], 0, v[90:91]
	global_load_dword v102, v[80:81], off nt
	global_load_dword v103, v[78:79], off nt
	global_load_dword v104, v[84:85], off nt
	global_load_dword v105, v[82:83], off nt
	global_load_dword v106, v[88:89], off nt
	global_load_dword v107, v[86:87], off nt
	global_load_dword v108, v[92:93], off nt
	global_load_dword v109, v[90:91], off nt
	v_add_u32_e32 v80, s4, v60
	v_add_u32_e32 v82, s4, v59
	v_add_u32_e32 v84, s4, v62
	v_add_u32_e32 v90, s4, v63
	v_add_u32_e32 v92, s4, v66
	v_add_u32_e32 v78, s4, v57
	v_ashrrev_i32_e32 v81, 31, v80
	v_ashrrev_i32_e32 v85, 31, v84
	v_ashrrev_i32_e32 v83, 31, v82
	v_add_u32_e32 v86, s4, v61
	v_add_u32_e32 v88, s4, v64
	v_ashrrev_i32_e32 v93, 31, v92
	v_ashrrev_i32_e32 v91, 31, v90
	v_ashrrev_i32_e32 v79, 31, v78
	v_lshlrev_b64 v[80:81], 12, v[80:81]
	v_lshlrev_b64 v[82:83], 12, v[82:83]
	v_lshlrev_b64 v[84:85], 12, v[84:85]
	v_ashrrev_i32_e32 v89, 31, v88
	v_ashrrev_i32_e32 v87, 31, v86
	v_lshlrev_b64 v[90:91], 12, v[90:91]
	v_lshlrev_b64 v[92:93], 12, v[92:93]
	v_lshlrev_b64 v[78:79], 12, v[78:79]
	v_lshl_add_u64 v[80:81], v[76:77], 0, v[80:81]
	v_lshl_add_u64 v[84:85], v[76:77], 0, v[84:85]
	v_lshl_add_u64 v[82:83], v[76:77], 0, v[82:83]
	v_lshlrev_b64 v[86:87], 12, v[86:87]
	v_lshlrev_b64 v[88:89], 12, v[88:89]
	v_lshl_add_u64 v[92:93], v[76:77], 0, v[92:93]
	v_lshl_add_u64 v[90:91], v[76:77], 0, v[90:91]
	v_lshl_add_u64 v[78:79], v[76:77], 0, v[78:79]
	v_lshl_add_u64 v[88:89], v[76:77], 0, v[88:89]
	v_lshl_add_u64 v[86:87], v[76:77], 0, v[86:87]
	global_load_dword v110, v[80:81], off nt
	global_load_dword v111, v[78:79], off nt
	global_load_dword v112, v[84:85], off nt
	global_load_dword v113, v[82:83], off nt
	global_load_dword v183, v[88:89], off nt
	global_load_dword v184, v[86:87], off nt
	s_nop 0
	global_load_dword v92, v[92:93], off nt
	s_nop 0
	global_load_dword v90, v[90:91], off nt
	v_add_u32_e32 v80, s4, v68
	v_add_u32_e32 v82, s4, v67
	v_add_u32_e32 v84, s4, v70
	v_add_u32_e32 v78, s4, v65
	v_ashrrev_i32_e32 v81, 31, v80
	v_ashrrev_i32_e32 v85, 31, v84
	v_ashrrev_i32_e32 v83, 31, v82
	v_add_u32_e32 v86, s4, v69
	v_add_u32_e32 v88, s4, v72
	v_ashrrev_i32_e32 v79, 31, v78
	v_lshlrev_b64 v[80:81], 12, v[80:81]
	v_lshlrev_b64 v[82:83], 12, v[82:83]
	v_lshlrev_b64 v[84:85], 12, v[84:85]
	v_ashrrev_i32_e32 v89, 31, v88
	v_ashrrev_i32_e32 v87, 31, v86
	v_lshlrev_b64 v[78:79], 12, v[78:79]
	v_lshl_add_u64 v[80:81], v[76:77], 0, v[80:81]
	v_lshl_add_u64 v[84:85], v[76:77], 0, v[84:85]
	v_lshl_add_u64 v[82:83], v[76:77], 0, v[82:83]
	v_lshlrev_b64 v[86:87], 12, v[86:87]
	v_lshlrev_b64 v[88:89], 12, v[88:89]
	v_lshl_add_u64 v[78:79], v[76:77], 0, v[78:79]
	v_lshl_add_u64 v[88:89], v[76:77], 0, v[88:89]
	v_lshl_add_u64 v[86:87], v[76:77], 0, v[86:87]
	global_load_dword v91, v[80:81], off nt
	global_load_dword v93, v[78:79], off nt
	s_nop 0
	global_load_dword v84, v[84:85], off nt
	s_nop 0
	global_load_dword v82, v[82:83], off nt
	s_nop 0
	global_load_dword v83, v[88:89], off nt
	global_load_dword v85, v[86:87], off nt
	v_add_u32_e32 v80, s4, v74
	v_add_u32_e32 v78, s4, v71
	v_ashrrev_i32_e32 v81, 31, v80
	v_ashrrev_i32_e32 v79, 31, v78
	v_lshlrev_b64 v[80:81], 12, v[80:81]
	v_lshlrev_b64 v[78:79], 12, v[78:79]
	v_lshl_add_u64 v[80:81], v[76:77], 0, v[80:81]
	global_load_dword v80, v[80:81], off nt
	v_lshl_add_u64 v[76:77], v[76:77], 0, v[78:79]
	global_load_dword v76, v[76:77], off nt
	v_add_u32_e32 v77, v73, v118
	s_waitcnt vmcnt(31)
; __device__ __forceinline__ void tr_item(const float* W, int ldw, int K, int k0, int sc0, bf16* WT, int dr0, const float* gain, float cs, LAS float* scr, int lane) {
;     ...
;     for (int i = 0; i < 32; ++i) { const int kk = 2 * i + (lane >> 5); const float g = gain ? gain[k0 + kk] * cs : cs;
;         scr[kk * 33 + (lane & 31)] = W[(size_t)(k0 + kk) * ldw + sc0 + (lane & 31)] * g; }
;     asm volatile("s_waitcnt lgkmcnt(0)" ::: "memory");
	ds_write_b32 v77, v94
	v_add_u32_e32 v77, v73, v119
	s_waitcnt vmcnt(30)
	ds_write_b32 v77, v95
	v_add_u32_e32 v77, v73, v120
	s_waitcnt vmcnt(29)
	ds_write_b32 v77, v96
	v_add_u32_e32 v77, v73, v121
	s_waitcnt vmcnt(28)
	ds_write_b32 v77, v97
	v_add_u32_e32 v77, v73, v122
	s_waitcnt vmcnt(27)
	ds_write_b32 v77, v98
	v_add_u32_e32 v77, v73, v123
	s_waitcnt vmcnt(26)
	ds_write_b32 v77, v99
	v_add_u32_e32 v77, v73, v124
	s_waitcnt vmcnt(25)
	ds_write_b32 v77, v100
	v_add_u32_e32 v77, v73, v126
	s_waitcnt vmcnt(24)
	ds_write_b32 v77, v101
	v_add_u32_e32 v77, v73, v127
	s_waitcnt vmcnt(23)
	ds_write_b32 v77, v102
	v_add_u32_e32 v77, v73, v128
	s_waitcnt vmcnt(22)
	ds_write_b32 v77, v103
	v_add_u32_e32 v77, v73, v129
	s_waitcnt vmcnt(21)
	ds_write_b32 v77, v104
	v_add_u32_e32 v77, v73, v130
	s_waitcnt vmcnt(20)
	ds_write_b32 v77, v105
	v_add_u32_e32 v77, v73, v131
	s_waitcnt vmcnt(19)
	ds_write_b32 v77, v106
	v_add_u32_e32 v77, v73, v132
	s_waitcnt vmcnt(18)
	ds_write_b32 v77, v107
	v_add_u32_e32 v77, v73, v133
	s_waitcnt vmcnt(17)
	ds_write_b32 v77, v108
	v_add_u32_e32 v77, v73, v134
	s_waitcnt vmcnt(16)
	ds_write_b32 v77, v109
	v_add_u32_e32 v77, v73, v135
	s_waitcnt vmcnt(15)
	ds_write_b32 v77, v110
	v_add_u32_e32 v77, v73, v136
	s_waitcnt vmcnt(14)
	ds_write_b32 v77, v111
	v_add_u32_e32 v77, v73, v137
	s_waitcnt vmcnt(13)
	ds_write_b32 v77, v112
	v_add_u32_e32 v77, v73, v138
	s_waitcnt vmcnt(12)
	ds_write_b32 v77, v113
	v_add_u32_e32 v77, v73, v139
	s_waitcnt vmcnt(11)
	ds_write_b32 v77, v183
	v_add_u32_e32 v77, v73, v140
	s_waitcnt vmcnt(10)
	ds_write_b32 v77, v184
	v_add_u32_e32 v77, v73, v141
	s_waitcnt vmcnt(9)
	ds_write_b32 v77, v92
	v_add_u32_e32 v77, v73, v142
	s_waitcnt vmcnt(8)
	ds_write_b32 v77, v90
	v_add_u32_e32 v77, v73, v143
	s_waitcnt vmcnt(7)
	ds_write_b32 v77, v91
	v_add_u32_e32 v77, v73, v144
	s_waitcnt vmcnt(6)
	ds_write_b32 v77, v93
	v_add_u32_e32 v77, v73, v145
	s_waitcnt vmcnt(5)
	ds_write_b32 v77, v84
	v_add_u32_e32 v77, v73, v146
	s_waitcnt vmcnt(4)
	ds_write_b32 v77, v82
	v_add_u32_e32 v77, v73, v147
	s_waitcnt vmcnt(3)
	ds_write_b32 v77, v83
	v_add_u32_e32 v77, v73, v148
	s_waitcnt vmcnt(2)
	ds_write_b32 v77, v85
	v_add_u32_e32 v77, v73, v149
	s_waitcnt vmcnt(1)
	ds_write_b32 v77, v80
	v_add_u32_e32 v77, v73, v150
	s_waitcnt vmcnt(0)
	ds_write_b32 v77, v76

; #define LAS __attribute__((address_space(3)))
; __device__ __forceinline__ void tr_item(const float* W, int ldw, int K, int k0, int sc0, bf16* WT, int dr0, const float* gain, float cs, LAS float* scr, int lane) {
; #pragma unroll 16
;     for (int i = 0; i < 32; ++i) { const int kk = 2 * i + (lane >> 5); const float g = gain ? gain[k0 + kk] * cs : cs;
;         scr[kk * 33 + (lane & 31)] = W[(size_t)(k0 + kk) * ldw + sc0 + (lane & 31)] * g; }
.LBB0_29:
	v_add_u32_e32 v81, s5, v78
	v_add_u32_e32 v80, 0xffffcc00, v81
	v_add_u32_e32 v82, 0xffffcc02, v81
	v_add_u32_e32 v84, 0xffffcc04, v81
	v_add_u32_e32 v86, 0xffffcc06, v81
	v_add_u32_e32 v88, 0xffffcc08, v81
	v_add_u32_e32 v90, 0xffffcc0a, v81
	v_add_u32_e32 v92, 0xffffcc0c, v81
	v_add_u32_e32 v94, 0xffffcc0e, v81
	v_add_u32_e32 v96, 0xffffcc10, v81
	v_add_u32_e32 v98, 0xffffcc12, v81
	v_add_u32_e32 v100, 0xffffcc14, v81
	v_add_u32_e32 v102, 0xffffcc16, v81
	v_add_u32_e32 v104, 0xffffcc18, v81
	v_add_u32_e32 v106, 0xffffcc1a, v81
	v_add_u32_e32 v108, 0xffffcc1c, v81
	v_add_u32_e32 v110, 0xffffcc1e, v81
	v_ashrrev_i32_e32 v81, 31, v80
	v_ashrrev_i32_e32 v83, 31, v82
	v_ashrrev_i32_e32 v85, 31, v84
	v_ashrrev_i32_e32 v87, 31, v86
	v_ashrrev_i32_e32 v89, 31, v88
	v_ashrrev_i32_e32 v91, 31, v90
	v_ashrrev_i32_e32 v93, 31, v92
	v_ashrrev_i32_e32 v95, 31, v94
	v_ashrrev_i32_e32 v97, 31, v96
	v_ashrrev_i32_e32 v99, 31, v98
	v_ashrrev_i32_e32 v101, 31, v100
	v_ashrrev_i32_e32 v103, 31, v102
	v_ashrrev_i32_e32 v105, 31, v104
	v_ashrrev_i32_e32 v107, 31, v106
	v_ashrrev_i32_e32 v109, 31, v108
	v_ashrrev_i32_e32 v111, 31, v110
	v_lshlrev_b64 v[80:81], 12, v[80:81]
	v_lshlrev_b64 v[82:83], 12, v[82:83]
	v_lshlrev_b64 v[84:85], 12, v[84:85]
	v_lshlrev_b64 v[86:87], 12, v[86:87]
	v_lshlrev_b64 v[88:89], 12, v[88:89]
	v_lshlrev_b64 v[90:91], 12, v[90:91]
	v_lshlrev_b64 v[92:93], 12, v[92:93]
	v_lshlrev_b64 v[94:95], 12, v[94:95]
	v_lshlrev_b64 v[96:97], 12, v[96:97]
	v_lshlrev_b64 v[98:99], 12, v[98:99]
	v_lshlrev_b64 v[100:101], 12, v[100:101]
	v_lshlrev_b64 v[102:103], 12, v[102:103]
	v_lshlrev_b64 v[104:105], 12, v[104:105]
	v_lshlrev_b64 v[106:107], 12, v[106:107]
	v_lshlrev_b64 v[108:109], 12, v[108:109]
	v_lshlrev_b64 v[110:111], 12, v[110:111]
	v_lshl_add_u64 v[80:81], v[76:77], 0, v[80:81]
	v_lshl_add_u64 v[82:83], v[76:77], 0, v[82:83]
	v_lshl_add_u64 v[84:85], v[76:77], 0, v[84:85]
	v_lshl_add_u64 v[86:87], v[76:77], 0, v[86:87]
	v_lshl_add_u64 v[88:89], v[76:77], 0, v[88:89]
	v_lshl_add_u64 v[90:91], v[76:77], 0, v[90:91]
	v_lshl_add_u64 v[92:93], v[76:77], 0, v[92:93]
	v_lshl_add_u64 v[94:95], v[76:77], 0, v[94:95]
	v_lshl_add_u64 v[96:97], v[76:77], 0, v[96:97]
	v_lshl_add_u64 v[98:99], v[76:77], 0, v[98:99]
	v_lshl_add_u64 v[100:101], v[76:77], 0, v[100:101]
	v_lshl_add_u64 v[102:103], v[76:77], 0, v[102:103]
	v_lshl_add_u64 v[104:105], v[76:77], 0, v[104:105]
	v_lshl_add_u64 v[106:107], v[76:77], 0, v[106:107]
	v_lshl_add_u64 v[108:109], v[76:77], 0, v[108:109]
	v_lshl_add_u64 v[110:111], v[76:77], 0, v[110:111]
	global_load_dword v80, v[80:81], off nt
	s_nop 0
	global_load_dword v81, v[82:83], off nt
	s_nop 0
	global_load_dword v82, v[84:85], off nt
	global_load_dword v83, v[86:87], off nt
	s_nop 0
	global_load_dword v84, v[88:89], off nt
	global_load_dword v85, v[90:91], off nt
	global_load_dword v86, v[92:93], off nt
	global_load_dword v87, v[94:95], off nt
	s_nop 0
	global_load_dword v88, v[96:97], off nt
	global_load_dword v89, v[98:99], off nt
	global_load_dword v90, v[100:101], off nt
	global_load_dword v91, v[102:103], off nt
	global_load_dword v92, v[104:105], off nt
	global_load_dword v93, v[106:107], off nt
	global_load_dword v94, v[108:109], off nt
	global_load_dword v95, v[110:111], off nt
	s_add_i32 s5, s5, 32
	v_add_u32_e32 v96, 0x400, v79
	v_add_u32_e32 v97, 0x800, v79
	v_add_u32_e32 v98, 0xc00, v79
	s_cmp_lg_u32 s5, 64
	s_waitcnt vmcnt(14)
	ds_write2_b32 v79, v80, v81 offset1:66
	s_waitcnt vmcnt(12)
	ds_write2_b32 v79, v82, v83 offset0:132 offset1:198
	s_waitcnt vmcnt(10)
	ds_write2_b32 v96, v84, v85 offset0:8 offset1:74
	s_waitcnt vmcnt(8)
	ds_write2_b32 v96, v86, v87 offset0:140 offset1:206
	s_waitcnt vmcnt(6)
	ds_write2_b32 v97, v88, v89 offset0:16 offset1:82
	s_waitcnt vmcnt(4)
	ds_write2_b32 v97, v90, v91 offset0:148 offset1:214
	s_waitcnt vmcnt(2)
	ds_write2_b32 v98, v92, v93 offset0:24 offset1:90
	s_waitcnt vmcnt(0)
	ds_write2_b32 v98, v94, v95 offset0:156 offset1:222
	v_add_u32_e32 v79, 0x1080, v79
	s_cbranch_scc1 .LBB0_29

; #define LAS __attribute__((address_space(3)))
; __device__ __forceinline__ void tr_item(const float* W, int ldw, int K, int k0, int sc0, bf16* WT, int dr0, const float* gain, float cs, LAS float* scr, int lane) {
; #pragma unroll 16
;     for (int i = 0; i < 32; ++i) { const int kk = 2 * i + (lane >> 5); const float g = gain ? gain[k0 + kk] * cs : cs;
;         scr[kk * 33 + (lane & 31)] = W[(size_t)(k0 + kk) * ldw + sc0 + (lane & 31)] * g; }
; __global__ void __launch_bounds__(NTHR, 2) hybrid_fwd(Args args) {
;     ...
;             if (r < I6) { const int kb = r / 176, nb = r % 176, n0 = 32 * nb, j = n0 >> 8, wi = n0 & 255; const int sc = wi < 128 ? 128 * j + wi : DFF + 128 * j + (wi - 128);
;                           tr_item(w_ffn_in, 2 * DFF, 1024, 64 * kb, sc, Wffi, n0, norm_ffn_g, 1.0f, scr, lane); continue; } r -= I6;
.LBB0_33:
	v_lshl_add_u64 v[112:113], v[76:77], 0, s[56:57]
	global_load_dword v112, v[112:113], off nt
	s_add_u32 s56, s56, 0xb0000
	s_addc_u32 s57, s57, 0
	s_add_u32 s58, s58, 0x80
	s_addc_u32 s59, s59, 0
	s_cmp_lg_u32 s56, 0x160000
	s_waitcnt vmcnt(0)
	v_mul_f32_e32 v112, v184, v112
	ds_write_b32 v183, v112 offset:3960
	v_add_u32_e32 v183, 0x1080, v183
	s_cbranch_scc0 .LBB0_66
.LBB0_34:
	v_cndmask_b32_e64 v112, 0, 1, s[46:47]
	v_mov_b32_e32 v184, 1.0
	v_cmp_ne_u32_e64 s[4:5], 1, v112
	s_andn2_b64 vcc, exec, s[46:47]
	v_mov_b32_e32 v112, 1.0
	s_cbranch_vccnz .LBB0_36
	v_lshl_add_u64 v[112:113], s[58:59], 0, v[110:111]
	global_load_dword v112, v[112:113], off nt
.LBB0_36:
	v_lshl_add_u64 v[186:187], v[108:109], 0, s[56:57]
	global_load_dword v113, v[186:187], off nt
	s_and_b64 vcc, exec, s[4:5]
	s_waitcnt vmcnt(0)
	v_mul_f32_e32 v112, v112, v113
	ds_write_b32 v183, v112
	v_lshl_add_u64 v[112:113], s[58:59], 0, v[78:79]
	s_cbranch_vccnz .LBB0_38
	global_load_dword v184, v[112:113], off offset:8 nt
.LBB0_38:
	v_lshl_add_u64 v[186:187], v[106:107], 0, s[56:57]
	global_load_dword v186, v[186:187], off nt
	v_mov_b32_e32 v185, 1.0
	s_and_b64 vcc, exec, s[4:5]
	s_waitcnt vmcnt(0)
	v_mul_f32_e32 v184, v184, v186
	ds_write_b32 v183, v184 offset:264
	v_mov_b32_e32 v184, 1.0
	s_cbranch_vccnz .LBB0_40
	global_load_dword v184, v[112:113], off offset:16 nt
.LBB0_40:
	v_lshl_add_u64 v[186:187], v[104:105], 0, s[56:57]
	global_load_dword v186, v[186:187], off nt
	s_and_b64 vcc, exec, s[4:5]
	s_waitcnt vmcnt(0)
	v_mul_f32_e32 v184, v184, v186
	ds_write_b32 v183, v184 offset:528
	s_cbranch_vccnz .LBB0_42
	global_load_dword v185, v[112:113], off offset:24 nt
.LBB0_42:
	v_lshl_add_u64 v[186:187], v[102:103], 0, s[56:57]
	global_load_dword v186, v[186:187], off nt
	v_mov_b32_e32 v184, 1.0
	s_and_b64 vcc, exec, s[4:5]
	s_waitcnt vmcnt(0)
	v_mul_f32_e32 v185, v185, v186
	ds_write_b32 v183, v185 offset:792
	v_mov_b32_e32 v185, 1.0
	s_cbranch_vccnz .LBB0_44
	global_load_dword v185, v[112:113], off offset:32 nt
.LBB0_44:
	v_lshl_add_u64 v[186:187], v[100:101], 0, s[56:57]
	global_load_dword v186, v[186:187], off nt
	s_and_b64 vcc, exec, s[4:5]
	s_waitcnt vmcnt(0)
	v_mul_f32_e32 v185, v185, v186
	ds_write_b32 v183, v185 offset:1056
	s_cbranch_vccnz .LBB0_46
	global_load_dword v184, v[112:113], off offset:40 nt
.LBB0_46:
	v_lshl_add_u64 v[186:187], v[98:99], 0, s[56:57]
	global_load_dword v186, v[186:187], off nt
	v_mov_b32_e32 v185, 1.0
	s_and_b64 vcc, exec, s[4:5]
	s_waitcnt vmcnt(0)
	v_mul_f32_e32 v184, v184, v186
	ds_write_b32 v183, v184 offset:1320
	v_mov_b32_e32 v184, 1.0
	s_cbranch_vccnz .LBB0_48
	global_load_dword v184, v[112:113], off offset:48 nt
.LBB0_48:
	v_lshl_add_u64 v[186:187], v[96:97], 0, s[56:57]
	global_load_dword v186, v[186:187], off nt
	s_and_b64 vcc, exec, s[4:5]
	s_waitcnt vmcnt(0)
	v_mul_f32_e32 v184, v184, v186
	ds_write_b32 v183, v184 offset:1584
	s_cbranch_vccnz .LBB0_50
	global_load_dword v185, v[112:113], off offset:56 nt
.LBB0_50:
	v_lshl_add_u64 v[186:187], v[94:95], 0, s[56:57]
	global_load_dword v186, v[186:187], off nt
	v_mov_b32_e32 v184, 1.0
	s_and_b64 vcc, exec, s[4:5]
	s_waitcnt vmcnt(0)
	v_mul_f32_e32 v185, v185, v186
	ds_write_b32 v183, v185 offset:1848
	v_mov_b32_e32 v185, 1.0
	s_cbranch_vccnz .LBB0_52
	global_load_dword v185, v[112:113], off offset:64 nt
.LBB0_52:
	v_lshl_add_u64 v[186:187], v[92:93], 0, s[56:57]
	global_load_dword v186, v[186:187], off nt
	s_and_b64 vcc, exec, s[4:5]
	s_waitcnt vmcnt(0)
	v_mul_f32_e32 v185, v185, v186
	ds_write_b32 v183, v185 offset:2112
	s_cbranch_vccnz .LBB0_54
	global_load_dword v184, v[112:113], off offset:72 nt
.LBB0_54:
	v_lshl_add_u64 v[186:187], v[90:91], 0, s[56:57]
	global_load_dword v186, v[186:187], off nt
	v_mov_b32_e32 v185, 1.0
	s_and_b64 vcc, exec, s[4:5]
	s_waitcnt vmcnt(0)
	v_mul_f32_e32 v184, v184, v186
	ds_write_b32 v183, v184 offset:2376
	v_mov_b32_e32 v184, 1.0
	s_cbranch_vccnz .LBB0_56
	global_load_dword v184, v[112:113], off offset:80 nt
.LBB0_56:
	v_lshl_add_u64 v[186:187], v[88:89], 0, s[56:57]
	global_load_dword v186, v[186:187], off nt
	s_and_b64 vcc, exec, s[4:5]
	s_waitcnt vmcnt(0)
	v_mul_f32_e32 v184, v184, v186
	ds_write_b32 v183, v184 offset:2640
	s_cbranch_vccnz .LBB0_58
	global_load_dword v185, v[112:113], off offset:88 nt
.LBB0_58:
	v_lshl_add_u64 v[186:187], v[86:87], 0, s[56:57]
	global_load_dword v184, v[186:187], off nt
	v_mov_b32_e32 v186, 1.0
	s_and_b64 vcc, exec, s[4:5]
	s_waitcnt vmcnt(0)
	v_mul_f32_e32 v184, v185, v184
	ds_write_b32 v183, v184 offset:2904
	v_mov_b32_e32 v184, 1.0
	s_cbranch_vccnz .LBB0_60
	global_load_dword v184, v[112:113], off offset:96 nt
.LBB0_60:
	v_lshl_add_u64 v[188:189], v[84:85], 0, s[56:57]
	global_load_dword v185, v[188:189], off nt
	s_and_b64 vcc, exec, s[4:5]
	s_waitcnt vmcnt(0)
	v_mul_f32_e32 v184, v184, v185
	ds_write_b32 v183, v184 offset:3168
	s_cbranch_vccnz .LBB0_62
	global_load_dword v186, v[112:113], off offset:104 nt
.LBB0_62:
	v_lshl_add_u64 v[184:185], v[82:83], 0, s[56:57]
	global_load_dword v185, v[184:185], off nt
	v_mov_b32_e32 v184, 1.0
	s_and_b64 vcc, exec, s[4:5]
	s_waitcnt vmcnt(0)
	v_mul_f32_e32 v185, v186, v185
	ds_write_b32 v183, v185 offset:3432
	v_mov_b32_e32 v185, 1.0
	s_cbranch_vccnz .LBB0_64
	global_load_dword v185, v[112:113], off offset:112 nt
.LBB0_64:
	v_lshl_add_u64 v[186:187], v[80:81], 0, s[56:57]
	global_load_dword v186, v[186:187], off nt
	s_and_b64 vcc, exec, s[4:5]
	s_waitcnt vmcnt(0)
	v_mul_f32_e32 v185, v185, v186
	ds_write_b32 v183, v185 offset:3696
	s_cbranch_vccnz .LBB0_33
	global_load_dword v184, v[112:113], off offset:120 nt
	s_branch .LBB0_33

; __device__ __forceinline__ void tr_item(const float* W, int ldw, int K, int k0, int sc0, bf16* WT, int dr0, const float* gain, float cs, LAS float* scr, int lane) {
; #pragma unroll 16
;     for (int i = 0; i < 32; ++i) { const int kk = 2 * i + (lane >> 5); const float g = gain ? gain[k0 + kk] * cs : cs;
;         scr[kk * 33 + (lane & 31)] = W[(size_t)(k0 + kk) * ldw + sc0 + (lane & 31)] * g; }
.LBB0_68:
	s_andn2_b64 vcc, exec, s[4:5]
	s_cbranch_vccnz .LBB0_70
	s_lshl_b32 s4, s70, 1
	s_and_b32 s4, s4, 0x1fc0
	s_addk_i32 s4, 0xe400
	s_lshl_b32 s5, s70, 5
	s_and_b32 s56, s5, 0x3e0
	v_add_u32_e32 v80, s4, v2
	s_lshl_b32 s44, s56, 2
	v_add_u32_e32 v78, s4, v1
	v_ashrrev_i32_e32 v81, 31, v80
	v_add_u32_e32 v82, s4, v3
	v_add_u32_e32 v84, s4, v46
	v_add_u32_e32 v86, s4, v33
	v_add_u32_e32 v88, s4, v48
	v_add_u32_e32 v90, s4, v47
	v_add_u32_e32 v92, s4, v50
	v_lshl_add_u64 v[76:77], v[10:11], 0, s[44:45]
	v_ashrrev_i32_e32 v79, 31, v78
	v_lshlrev_b64 v[80:81], 12, v[80:81]
	v_ashrrev_i32_e32 v85, 31, v84
	v_ashrrev_i32_e32 v83, 31, v82
	v_ashrrev_i32_e32 v89, 31, v88
	v_ashrrev_i32_e32 v87, 31, v86
	v_ashrrev_i32_e32 v93, 31, v92
	v_ashrrev_i32_e32 v91, 31, v90
	v_lshlrev_b64 v[78:79], 12, v[78:79]
	v_lshl_add_u64 v[80:81], v[76:77], 0, v[80:81]
	v_lshlrev_b64 v[82:83], 12, v[82:83]
	v_lshlrev_b64 v[84:85], 12, v[84:85]
	v_lshlrev_b64 v[86:87], 12, v[86:87]
	v_lshlrev_b64 v[88:89], 12, v[88:89]
	v_lshlrev_b64 v[90:91], 12, v[90:91]
	v_lshlrev_b64 v[92:93], 12, v[92:93]
	v_lshl_add_u64 v[78:79], v[76:77], 0, v[78:79]
	v_lshl_add_u64 v[84:85], v[76:77], 0, v[84:85]
	v_lshl_add_u64 v[82:83], v[76:77], 0, v[82:83]
	v_lshl_add_u64 v[88:89], v[76:77], 0, v[88:89]
	v_lshl_add_u64 v[86:87], v[76:77], 0, v[86:87]
	v_lshl_add_u64 v[92:93], v[76:77], 0, v[92:93]
	v_lshl_add_u64 v[90:91], v[76:77], 0, v[90:91]
	global_load_dword v94, v[80:81], off nt
	global_load_dword v95, v[78:79], off nt
	global_load_dword v96, v[84:85], off nt
	global_load_dword v97, v[82:83], off nt
	global_load_dword v98, v[88:89], off nt
	global_load_dword v99, v[86:87], off nt
	global_load_dword v100, v[92:93], off nt
	global_load_dword v101, v[90:91], off nt
	v_add_u32_e32 v80, s4, v52
	v_add_u32_e32 v78, s4, v49
	v_ashrrev_i32_e32 v81, 31, v80
	v_add_u32_e32 v82, s4, v51
	v_add_u32_e32 v84, s4, v54
	v_add_u32_e32 v86, s4, v53
	v_add_u32_e32 v88, s4, v56
	v_add_u32_e32 v90, s4, v55
	v_add_u32_e32 v92, s4, v58
	v_ashrrev_i32_e32 v79, 31, v78
	v_lshlrev_b64 v[80:81], 12, v[80:81]
	v_ashrrev_i32_e32 v85, 31, v84
	v_ashrrev_i32_e32 v83, 31, v82
	v_ashrrev_i32_e32 v89, 31, v88
	v_ashrrev_i32_e32 v87, 31, v86
	v_ashrrev_i32_e32 v93, 31, v92
	v_ashrrev_i32_e32 v91, 31, v90
	v_lshlrev_b64 v[78:79], 12, v[78:79]
	v_lshl_add_u64 v[80:81], v[76:77], 0, v[80:81]
	v_lshlrev_b64 v[82:83], 12, v[82:83]
	v_lshlrev_b64 v[84:85], 12, v[84:85]
	v_lshlrev_b64 v[86:87], 12, v[86:87]
	v_lshlrev_b64 v[88:89], 12, v[88:89]
	v_lshlrev_b64 v[90:91], 12, v[90:91]
	v_lshlrev_b64 v[92:93], 12, v[92:93]
	v_lshl_add_u64 v[78:79], v[76:77], 0, v[78:79]
	v_lshl_add_u64 v[84:85], v[76:77], 0, v[84:85]
	v_lshl_add_u64 v[82:83], v[76:77], 0, v[82:83]
	v_lshl_add_u64 v[88:89], v[76:77], 0, v[88:89]
	v_lshl_add_u64 v[86:87], v[76:77], 0, v[86:87]
	v_lshl_add_u64 v[92:93], v[76:77], 0, v[92:93]
	v_lshl_add_u64 v[90:91], v[76:77], 0, v[90:91]
	global_load_dword v102, v[80:81], off nt
	global_load_dword v103, v[78:79], off nt
	global_load_dword v104, v[84:85], off nt
	global_load_dword v105, v[82:83], off nt
	global_load_dword v106, v[88:89], off nt
	global_load_dword v107, v[86:87], off nt
	global_load_dword v108, v[92:93], off nt
	global_load_dword v109, v[90:91], off nt
	v_add_u32_e32 v80, s4, v60
	v_add_u32_e32 v82, s4, v59
	v_add_u32_e32 v84, s4, v62
	v_add_u32_e32 v90, s4, v63
	v_add_u32_e32 v92, s4, v66
	v_add_u32_e32 v78, s4, v57
	v_ashrrev_i32_e32 v81, 31, v80
	v_ashrrev_i32_e32 v85, 31, v84
	v_ashrrev_i32_e32 v83, 31, v82
	v_add_u32_e32 v86, s4, v61
	v_add_u32_e32 v88, s4, v64
	v_ashrrev_i32_e32 v93, 31, v92
	v_ashrrev_i32_e32 v91, 31, v90
	v_ashrrev_i32_e32 v79, 31, v78
	v_lshlrev_b64 v[80:81], 12, v[80:81]
	v_lshlrev_b64 v[82:83], 12, v[82:83]
	v_lshlrev_b64 v[84:85], 12, v[84:85]
	v_ashrrev_i32_e32 v89, 31, v88
	v_ashrrev_i32_e32 v87, 31, v86
	v_lshlrev_b64 v[90:91], 12, v[90:91]
	v_lshlrev_b64 v[92:93], 12, v[92:93]
	v_lshlrev_b64 v[78:79], 12, v[78:79]
	v_lshl_add_u64 v[80:81], v[76:77], 0, v[80:81]
	v_lshl_add_u64 v[84:85], v[76:77], 0, v[84:85]
	v_lshl_add_u64 v[82:83], v[76:77], 0, v[82:83]
	v_lshlrev_b64 v[86:87], 12, v[86:87]
	v_lshlrev_b64 v[88:89], 12, v[88:89]
	v_lshl_add_u64 v[92:93], v[76:77], 0, v[92:93]
	v_lshl_add_u64 v[90:91], v[76:77], 0, v[90:91]
	v_lshl_add_u64 v[78:79], v[76:77], 0, v[78:79]
	v_lshl_add_u64 v[88:89], v[76:77], 0, v[88:89]
	v_lshl_add_u64 v[86:87], v[76:77], 0, v[86:87]
	global_load_dword v110, v[80:81], off nt
	global_load_dword v111, v[78:79], off nt
	global_load_dword v112, v[84:85], off nt
	global_load_dword v113, v[82:83], off nt
	global_load_dword v183, v[88:89], off nt
	global_load_dword v184, v[86:87], off nt
	s_nop 0
	global_load_dword v92, v[92:93], off nt
	s_nop 0
	global_load_dword v90, v[90:91], off nt
	v_add_u32_e32 v80, s4, v68
	v_add_u32_e32 v82, s4, v67
	v_add_u32_e32 v84, s4, v70
	v_add_u32_e32 v78, s4, v65
	v_ashrrev_i32_e32 v81, 31, v80
	v_ashrrev_i32_e32 v85, 31, v84
	v_ashrrev_i32_e32 v83, 31, v82
	v_add_u32_e32 v86, s4, v69
	v_add_u32_e32 v88, s4, v72
	v_ashrrev_i32_e32 v79, 31, v78
	v_lshlrev_b64 v[80:81], 12, v[80:81]
	v_lshlrev_b64 v[82:83], 12, v[82:83]
	v_lshlrev_b64 v[84:85], 12, v[84:85]
	v_ashrrev_i32_e32 v89, 31, v88
	v_ashrrev_i32_e32 v87, 31, v86
	v_lshlrev_b64 v[78:79], 12, v[78:79]
	v_lshl_add_u64 v[80:81], v[76:77], 0, v[80:81]
	v_lshl_add_u64 v[84:85], v[76:77], 0, v[84:85]
	v_lshl_add_u64 v[82:83], v[76:77], 0, v[82:83]
	v_lshlrev_b64 v[86:87], 12, v[86:87]
	v_lshlrev_b64 v[88:89], 12, v[88:89]
	v_lshl_add_u64 v[78:79], v[76:77], 0, v[78:79]
	v_lshl_add_u64 v[88:89], v[76:77], 0, v[88:89]
	v_lshl_add_u64 v[86:87], v[76:77], 0, v[86:87]
	global_load_dword v91, v[80:81], off nt
	global_load_dword v93, v[78:79], off nt
	s_nop 0
	global_load_dword v84, v[84:85], off nt
	s_nop 0
	global_load_dword v82, v[82:83], off nt
	s_nop 0
	global_load_dword v83, v[88:89], off nt
	global_load_dword v85, v[86:87], off nt
	v_add_u32_e32 v80, s4, v74
	v_add_u32_e32 v78, s4, v71
	v_ashrrev_i32_e32 v81, 31, v80
	v_ashrrev_i32_e32 v79, 31, v78
	v_lshlrev_b64 v[80:81], 12, v[80:81]
	v_lshlrev_b64 v[78:79], 12, v[78:79]
	v_lshl_add_u64 v[80:81], v[76:77], 0, v[80:81]
	global_load_dword v80, v[80:81], off nt
	v_lshl_add_u64 v[76:77], v[76:77], 0, v[78:79]
	global_load_dword v76, v[76:77], off nt
	v_add_u32_e32 v77, v73, v118
	s_waitcnt vmcnt(31)
; #define LAS __attribute__((address_space(3)))
; __device__ __forceinline__ unsigned pk2(float lo, float hi) { return pg8::cvt_pk_bf16(lo, hi); }
; __device__ __forceinline__ void tr_item(const float* W, int ldw, int K, int k0, int sc0, bf16* WT, int dr0, const float* gain, float cs, LAS float* scr, int lane) {
;     ...
;         scr[kk * 33 + (lane & 31)] = W[(size_t)(k0 + kk) * ldw + sc0 + (lane & 31)] * g; }
;     asm volatile("s_waitcnt lgkmcnt(0)" ::: "memory");
;     const int c = lane & 7;
; #pragma unroll
;     for (int j = 0; j < 4; ++j) { const int n = (lane >> 3) + 8 * j; const LAS float* s = scr + (8 * c) * 33 + n;
;         u32x4 o; o.x = pk2(s[0 * 33], s[1 * 33]); o.y = pk2(s[2 * 33], s[3 * 33]); o.z = pk2(s[4 * 33], s[5 * 33]); o.w = pk2(s[6 * 33], s[7 * 33]);
;         *(u32x4*)(WT + (size_t)(dr0 + n) * K + k0 + 8 * c) = o; }
	ds_write_b32 v77, v94
	v_add_u32_e32 v77, v73, v119
	s_waitcnt vmcnt(30)
	ds_write_b32 v77, v95
	v_add_u32_e32 v77, v73, v120
	s_waitcnt vmcnt(29)
	ds_write_b32 v77, v96
	v_add_u32_e32 v77, v73, v121
	s_waitcnt vmcnt(28)
	ds_write_b32 v77, v97
	v_add_u32_e32 v77, v73, v122
	s_waitcnt vmcnt(27)
	ds_write_b32 v77, v98
	v_add_u32_e32 v77, v73, v123
	s_waitcnt vmcnt(26)
	ds_write_b32 v77, v99
	v_add_u32_e32 v77, v73, v124
	s_waitcnt vmcnt(25)
	ds_write_b32 v77, v100
	v_add_u32_e32 v77, v73, v126
	s_waitcnt vmcnt(24)
	ds_write_b32 v77, v101
	v_add_u32_e32 v77, v73, v127
	s_waitcnt vmcnt(23)
	ds_write_b32 v77, v102
	v_add_u32_e32 v77, v73, v128
	s_waitcnt vmcnt(22)
	ds_write_b32 v77, v103
	v_add_u32_e32 v77, v73, v129
	s_waitcnt vmcnt(21)
	ds_write_b32 v77, v104
	v_add_u32_e32 v77, v73, v130
	s_waitcnt vmcnt(20)
	ds_write_b32 v77, v105
	v_add_u32_e32 v77, v73, v131
	s_waitcnt vmcnt(19)
	ds_write_b32 v77, v106
	v_add_u32_e32 v77, v73, v132
	s_waitcnt vmcnt(18)
	ds_write_b32 v77, v107
	v_add_u32_e32 v77, v73, v133
	s_waitcnt vmcnt(17)
	ds_write_b32 v77, v108
	v_add_u32_e32 v77, v73, v134
	s_waitcnt vmcnt(16)
	ds_write_b32 v77, v109
	v_add_u32_e32 v77, v73, v135
	s_mov_b32 s5, s45
	s_waitcnt vmcnt(15)
	ds_write_b32 v77, v110
	v_add_u32_e32 v77, v73, v136
	s_waitcnt vmcnt(14)
	ds_write_b32 v77, v111
	v_add_u32_e32 v77, v73, v137
	s_waitcnt vmcnt(13)
	ds_write_b32 v77, v112
	v_add_u32_e32 v77, v73, v138
	s_waitcnt vmcnt(12)
	ds_write_b32 v77, v113
	v_add_u32_e32 v77, v73, v139
	s_waitcnt vmcnt(11)
	ds_write_b32 v77, v183
	v_add_u32_e32 v77, v73, v140
	s_waitcnt vmcnt(10)
	ds_write_b32 v77, v184
	v_add_u32_e32 v77, v73, v141
	s_waitcnt vmcnt(9)
	ds_write_b32 v77, v92
	v_add_u32_e32 v77, v73, v142
	s_waitcnt vmcnt(8)
	ds_write_b32 v77, v90
	v_add_u32_e32 v77, v73, v143
	s_waitcnt vmcnt(7)
	ds_write_b32 v77, v91
	v_add_u32_e32 v77, v73, v144
	s_waitcnt vmcnt(6)
	ds_write_b32 v77, v93
	v_add_u32_e32 v77, v73, v145
	s_waitcnt vmcnt(5)
	ds_write_b32 v77, v84
	v_add_u32_e32 v77, v73, v146
	s_waitcnt vmcnt(4)
	ds_write_b32 v77, v82
	v_add_u32_e32 v77, v73, v147
	s_waitcnt vmcnt(3)
	ds_write_b32 v77, v83
	v_add_u32_e32 v77, v73, v148
	s_waitcnt vmcnt(2)
	ds_write_b32 v77, v85
	v_add_u32_e32 v77, v73, v149
	v_lshl_add_u64 v[82:83], s[4:5], 1, v[12:13]
	s_waitcnt vmcnt(1)
	ds_write_b32 v77, v80
	v_add_u32_e32 v77, v73, v150
	s_waitcnt vmcnt(0)
	ds_write_b32 v77, v76
	s_waitcnt lgkmcnt(0)
	ds_read2_b32 v[76:77], v75 offset1:33
	s_waitcnt lgkmcnt(0)
	v_cvt_pk_bf16_f32 v76, v76, v77
	ds_read2_b32 v[78:79], v75 offset0:66 offset1:99
	s_waitcnt lgkmcnt(0)
	v_cvt_pk_bf16_f32 v77, v78, v79
	ds_read2_b32 v[78:79], v75 offset0:132 offset1:165
	s_waitcnt lgkmcnt(0)
	v_cvt_pk_bf16_f32 v78, v78, v79
	ds_read2_b32 v[80:81], v75 offset0:198 offset1:231
	s_waitcnt lgkmcnt(0)
	v_cvt_pk_bf16_f32 v79, v80, v81
	v_add_u32_e32 v80, s56, v0
	v_ashrrev_i32_e32 v81, 31, v80
	v_lshlrev_b64 v[80:81], 10, v[80:81]
	v_lshl_add_u64 v[80:81], v[82:83], 0, v[80:81]
	ds_read2_b32 v[84:85], v75 offset0:8 offset1:41
	global_store_dwordx4 v[80:81], v[76:79], off
	s_waitcnt lgkmcnt(0)
	s_nop 0
	v_cvt_pk_bf16_f32 v76, v84, v85
	ds_read2_b32 v[78:79], v75 offset0:74 offset1:107
	s_waitcnt lgkmcnt(0)
	v_cvt_pk_bf16_f32 v77, v78, v79
	ds_read2_b32 v[78:79], v75 offset0:140 offset1:173
	s_waitcnt lgkmcnt(0)
	v_cvt_pk_bf16_f32 v78, v78, v79
	ds_read2_b32 v[80:81], v75 offset0:206 offset1:239
	s_waitcnt lgkmcnt(0)
	v_cvt_pk_bf16_f32 v79, v80, v81
	v_add_u32_e32 v80, s56, v114
	v_ashrrev_i32_e32 v81, 31, v80
	v_lshlrev_b64 v[80:81], 10, v[80:81]
	v_lshl_add_u64 v[80:81], v[82:83], 0, v[80:81]
	ds_read2_b32 v[84:85], v75 offset0:16 offset1:49
	global_store_dwordx4 v[80:81], v[76:79], off
	s_waitcnt lgkmcnt(0)
	s_nop 0
	v_cvt_pk_bf16_f32 v76, v84, v85
	ds_read2_b32 v[78:79], v75 offset0:82 offset1:115
	s_waitcnt lgkmcnt(0)
	v_cvt_pk_bf16_f32 v77, v78, v79
	ds_read2_b32 v[78:79], v75 offset0:148 offset1:181
	s_waitcnt lgkmcnt(0)
	v_cvt_pk_bf16_f32 v78, v78, v79
	ds_read2_b32 v[80:81], v75 offset0:214 offset1:247
	s_waitcnt lgkmcnt(0)
	v_cvt_pk_bf16_f32 v79, v80, v81
	v_add_u32_e32 v80, s56, v115
	v_ashrrev_i32_e32 v81, 31, v80
	v_lshlrev_b64 v[80:81], 10, v[80:81]
	v_lshl_add_u64 v[80:81], v[82:83], 0, v[80:81]
	ds_read2_b32 v[84:85], v75 offset0:24 offset1:57
	global_store_dwordx4 v[80:81], v[76:79], off
	s_waitcnt lgkmcnt(0)
	s_nop 0
	v_cvt_pk_bf16_f32 v76, v84, v85
	ds_read2_b32 v[78:79], v75 offset0:90 offset1:123
	s_waitcnt lgkmcnt(0)
	v_cvt_pk_bf16_f32 v77, v78, v79
	ds_read2_b32 v[78:79], v75 offset0:156 offset1:189
	s_waitcnt lgkmcnt(0)
	v_cvt_pk_bf16_f32 v78, v78, v79
	ds_read2_b32 v[80:81], v75 offset0:222 offset1:255
	s_waitcnt lgkmcnt(0)
	v_cvt_pk_bf16_f32 v79, v80, v81
	v_add_u32_e32 v80, s56, v116
	v_ashrrev_i32_e32 v81, 31, v80
	v_lshlrev_b64 v[80:81], 10, v[80:81]
	v_lshl_add_u64 v[80:81], v[82:83], 0, v[80:81]
	global_store_dwordx4 v[80:81], v[76:79], off
	s_waitcnt lgkmcnt(0)

; __device__ __forceinline__ void tr_item(const float* W, int ldw, int K, int k0, int sc0, bf16* WT, int dr0, const float* gain, float cs, LAS float* scr, int lane) {
; #pragma unroll 16
;     for (int i = 0; i < 32; ++i) { const int kk = 2 * i + (lane >> 5); const float g = gain ? gain[k0 + kk] * cs : cs;
;         scr[kk * 33 + (lane & 31)] = W[(size_t)(k0 + kk) * ldw + sc0 + (lane & 31)] * g; }
.LBB0_73:
	v_lshl_add_u64 v[184:185], v[76:77], 0, s[56:57]
	global_load_dword v183, v[184:185], off nt
	s_add_u32 s56, s56, 0x20000
	s_addc_u32 s57, s57, 0
	v_lshl_add_u64 v[78:79], v[78:79], 0, s[54:55]
	s_cmp_lg_u32 s56, 0x40000
	v_lshl_add_u64 v[86:87], v[86:87], 0, s[54:55]
	s_waitcnt vmcnt(0)
	v_mul_f32_e32 v113, v113, v183
	ds_write_b32 v112, v113 offset:3960
	v_add_u32_e32 v112, 0x1080, v112
	s_cbranch_scc0 .LBB0_106
.LBB0_74:
	v_cndmask_b32_e64 v183, 0, 1, s[48:49]
	v_mov_b32_e32 v113, 1.0
	v_cmp_ne_u32_e64 s[4:5], 1, v183
	s_andn2_b64 vcc, exec, s[48:49]
	v_mov_b32_e32 v183, 1.0
	s_cbranch_vccnz .LBB0_76
	global_load_dword v183, v[78:79], off nt
.LBB0_76:
	v_lshl_add_u64 v[184:185], v[82:83], 0, s[56:57]
	global_load_dword v184, v[184:185], off nt
	s_and_b64 vcc, exec, s[4:5]
	s_waitcnt vmcnt(0)
	v_mul_f32_e32 v183, v183, v184
	ds_write_b32 v112, v183
	s_cbranch_vccnz .LBB0_78
	global_load_dword v113, v[86:87], off nt
.LBB0_78:
	v_lshl_add_u64 v[184:185], v[90:91], 0, s[56:57]
	global_load_dword v184, v[184:185], off nt
	v_mov_b32_e32 v183, 1.0
	s_and_b64 vcc, exec, s[4:5]
	s_waitcnt vmcnt(0)
	v_mul_f32_e32 v113, v113, v184
	ds_write_b32 v112, v113 offset:264
	v_mov_b32_e32 v113, 1.0
	s_cbranch_vccnz .LBB0_80
	global_load_dword v113, v[86:87], off offset:8 nt
.LBB0_80:
	v_lshl_add_u64 v[184:185], v[94:95], 0, s[56:57]
	global_load_dword v184, v[184:185], off nt
	s_and_b64 vcc, exec, s[4:5]
	s_waitcnt vmcnt(0)
	v_mul_f32_e32 v113, v113, v184
	ds_write_b32 v112, v113 offset:528
	s_cbranch_vccnz .LBB0_82
	global_load_dword v183, v[86:87], off offset:16 nt
.LBB0_82:
	v_lshl_add_u64 v[184:185], v[98:99], 0, s[56:57]
	global_load_dword v184, v[184:185], off nt
	v_mov_b32_e32 v113, 1.0
	s_and_b64 vcc, exec, s[4:5]
	s_waitcnt vmcnt(0)
	v_mul_f32_e32 v183, v183, v184
	ds_write_b32 v112, v183 offset:792
	v_mov_b32_e32 v183, 1.0
	s_cbranch_vccnz .LBB0_84
	global_load_dword v183, v[86:87], off offset:24 nt
.LBB0_84:
	v_lshl_add_u64 v[184:185], v[102:103], 0, s[56:57]
	global_load_dword v184, v[184:185], off nt
	s_and_b64 vcc, exec, s[4:5]
	s_waitcnt vmcnt(0)
	v_mul_f32_e32 v183, v183, v184
	ds_write_b32 v112, v183 offset:1056
	s_cbranch_vccnz .LBB0_86
	global_load_dword v113, v[86:87], off offset:32 nt
.LBB0_86:
	v_lshl_add_u64 v[184:185], v[106:107], 0, s[56:57]
	global_load_dword v184, v[184:185], off nt
	v_mov_b32_e32 v183, 1.0
	s_and_b64 vcc, exec, s[4:5]
	s_waitcnt vmcnt(0)
	v_mul_f32_e32 v113, v113, v184
	ds_write_b32 v112, v113 offset:1320
	v_mov_b32_e32 v113, 1.0
	s_cbranch_vccnz .LBB0_88
	global_load_dword v113, v[86:87], off offset:40 nt
.LBB0_88:
	v_lshl_add_u64 v[184:185], v[110:111], 0, s[56:57]
	global_load_dword v184, v[184:185], off nt
	s_and_b64 vcc, exec, s[4:5]
	s_waitcnt vmcnt(0)
	v_mul_f32_e32 v113, v113, v184
	ds_write_b32 v112, v113 offset:1584
	s_cbranch_vccnz .LBB0_90
	global_load_dword v183, v[86:87], off offset:48 nt
.LBB0_90:
	v_lshl_add_u64 v[184:185], v[108:109], 0, s[56:57]
	global_load_dword v184, v[184:185], off nt
	v_mov_b32_e32 v113, 1.0
	s_and_b64 vcc, exec, s[4:5]
	s_waitcnt vmcnt(0)
	v_mul_f32_e32 v183, v183, v184
	ds_write_b32 v112, v183 offset:1848
	v_mov_b32_e32 v183, 1.0
	s_cbranch_vccnz .LBB0_92
	global_load_dword v183, v[86:87], off offset:56 nt
.LBB0_92:
	v_lshl_add_u64 v[184:185], v[104:105], 0, s[56:57]
	global_load_dword v184, v[184:185], off nt
	s_and_b64 vcc, exec, s[4:5]
	s_waitcnt vmcnt(0)
	v_mul_f32_e32 v183, v183, v184
	ds_write_b32 v112, v183 offset:2112
	s_cbranch_vccnz .LBB0_94
	global_load_dword v113, v[86:87], off offset:64 nt
.LBB0_94:
	v_lshl_add_u64 v[184:185], v[100:101], 0, s[56:57]
	global_load_dword v184, v[184:185], off nt
	v_mov_b32_e32 v183, 1.0
	s_and_b64 vcc, exec, s[4:5]
	s_waitcnt vmcnt(0)
	v_mul_f32_e32 v113, v113, v184
	ds_write_b32 v112, v113 offset:2376
	v_mov_b32_e32 v113, 1.0
	s_cbranch_vccnz .LBB0_96
	global_load_dword v113, v[86:87], off offset:72 nt
.LBB0_96:
	v_lshl_add_u64 v[184:185], v[96:97], 0, s[56:57]
	global_load_dword v184, v[184:185], off nt
	s_and_b64 vcc, exec, s[4:5]
	s_waitcnt vmcnt(0)
	v_mul_f32_e32 v113, v113, v184
	ds_write_b32 v112, v113 offset:2640
	s_cbranch_vccnz .LBB0_98
	global_load_dword v183, v[86:87], off offset:80 nt
.LBB0_98:
	v_lshl_add_u64 v[184:185], v[92:93], 0, s[56:57]
	global_load_dword v113, v[184:185], off nt
	v_mov_b32_e32 v184, 1.0
	s_and_b64 vcc, exec, s[4:5]
	s_waitcnt vmcnt(0)
	v_mul_f32_e32 v113, v183, v113
	ds_write_b32 v112, v113 offset:2904
	v_mov_b32_e32 v113, 1.0
	s_cbranch_vccnz .LBB0_100
	global_load_dword v113, v[86:87], off offset:88 nt
.LBB0_100:
	v_lshl_add_u64 v[186:187], v[88:89], 0, s[56:57]
	global_load_dword v183, v[186:187], off nt
	s_and_b64 vcc, exec, s[4:5]
	s_waitcnt vmcnt(0)
	v_mul_f32_e32 v113, v113, v183
	ds_write_b32 v112, v113 offset:3168
	s_cbranch_vccnz .LBB0_102
	global_load_dword v184, v[86:87], off offset:96 nt
.LBB0_102:
	v_lshl_add_u64 v[186:187], v[84:85], 0, s[56:57]
	global_load_dword v183, v[186:187], off nt
	v_mov_b32_e32 v113, 1.0
	s_and_b64 vcc, exec, s[4:5]
	s_waitcnt vmcnt(0)
	v_mul_f32_e32 v183, v184, v183
	ds_write_b32 v112, v183 offset:3432
	v_mov_b32_e32 v183, 1.0
	s_cbranch_vccnz .LBB0_104
	global_load_dword v183, v[86:87], off offset:104 nt
.LBB0_104:
	v_lshl_add_u64 v[184:185], v[80:81], 0, s[56:57]
	global_load_dword v184, v[184:185], off nt
	s_and_b64 vcc, exec, s[4:5]
	s_waitcnt vmcnt(0)
	v_mul_f32_e32 v183, v183, v184
	ds_write_b32 v112, v183 offset:3696
	s_cbranch_vccnz .LBB0_73
	global_load_dword v113, v[86:87], off offset:112 nt
	s_branch .LBB0_73

; __device__ __forceinline__ void tr_item(const float* W, int ldw, int K, int k0, int sc0, bf16* WT, int dr0, const float* gain, float cs, LAS float* scr, int lane) {
; #pragma unroll 16
;     for (int i = 0; i < 32; ++i) { const int kk = 2 * i + (lane >> 5); const float g = gain ? gain[k0 + kk] * cs : cs;
;         scr[kk * 33 + (lane & 31)] = W[(size_t)(k0 + kk) * ldw + sc0 + (lane & 31)] * g; }
.LBB0_110:
	v_lshl_add_u64 v[184:185], v[76:77], 0, s[56:57]
	global_load_dword v183, v[184:185], off nt
	s_add_u32 s56, s56, 0x10000
	s_addc_u32 s57, s57, 0
	v_lshl_add_u64 v[78:79], v[78:79], 0, s[54:55]
	s_cmp_lg_u32 s56, 0x20000
	v_lshl_add_u64 v[86:87], v[86:87], 0, s[54:55]
	s_waitcnt vmcnt(0)
	v_mul_f32_e32 v113, v113, v183
	ds_write_b32 v112, v113 offset:3960
	v_add_u32_e32 v112, 0x1080, v112
	s_cbranch_scc0 .LBB0_143
.LBB0_111:
	v_cndmask_b32_e64 v183, 0, 1, s[50:51]
	v_mov_b32_e32 v113, 0x3e0293ee
	v_cmp_ne_u32_e64 s[4:5], 1, v183
	s_andn2_b64 vcc, exec, s[50:51]
	v_mov_b32_e32 v183, 0x3e0293ee
	s_cbranch_vccnz .LBB0_113
	global_load_dword v183, v[78:79], off nt
	s_waitcnt vmcnt(0)
	v_mul_f32_e32 v183, 0x3e0293ee, v183
.LBB0_113:
	v_lshl_add_u64 v[184:185], v[82:83], 0, s[56:57]
	global_load_dword v184, v[184:185], off nt
	s_and_b64 vcc, exec, s[4:5]
	s_waitcnt vmcnt(0)
	v_mul_f32_e32 v183, v183, v184
	ds_write_b32 v112, v183
	s_cbranch_vccnz .LBB0_115
	global_load_dword v113, v[86:87], off nt
	s_waitcnt vmcnt(0)
	v_mul_f32_e32 v113, 0x3e0293ee, v113
.LBB0_115:
	v_lshl_add_u64 v[184:185], v[90:91], 0, s[56:57]
	global_load_dword v184, v[184:185], off nt
	v_mov_b32_e32 v183, 0x3e0293ee
	s_and_b64 vcc, exec, s[4:5]
	s_waitcnt vmcnt(0)
	v_mul_f32_e32 v113, v113, v184
	ds_write_b32 v112, v113 offset:264
	v_mov_b32_e32 v113, 0x3e0293ee
	s_cbranch_vccnz .LBB0_117
	global_load_dword v113, v[86:87], off offset:8 nt
	s_waitcnt vmcnt(0)
	v_mul_f32_e32 v113, 0x3e0293ee, v113
.LBB0_117:
	v_lshl_add_u64 v[184:185], v[94:95], 0, s[56:57]
	global_load_dword v184, v[184:185], off nt
	s_and_b64 vcc, exec, s[4:5]
	s_waitcnt vmcnt(0)
	v_mul_f32_e32 v113, v113, v184
	ds_write_b32 v112, v113 offset:528
	s_cbranch_vccnz .LBB0_119
	global_load_dword v113, v[86:87], off offset:16 nt
	s_waitcnt vmcnt(0)
	v_mul_f32_e32 v183, 0x3e0293ee, v113
.LBB0_119:
	v_lshl_add_u64 v[184:185], v[98:99], 0, s[56:57]
	global_load_dword v184, v[184:185], off nt
	v_mov_b32_e32 v113, 0x3e0293ee
	s_and_b64 vcc, exec, s[4:5]
	s_waitcnt vmcnt(0)
	v_mul_f32_e32 v183, v183, v184
	ds_write_b32 v112, v183 offset:792
	v_mov_b32_e32 v183, 0x3e0293ee
	s_cbranch_vccnz .LBB0_121
	global_load_dword v183, v[86:87], off offset:24 nt
	s_waitcnt vmcnt(0)
	v_mul_f32_e32 v183, 0x3e0293ee, v183
.LBB0_121:
	v_lshl_add_u64 v[184:185], v[102:103], 0, s[56:57]
	global_load_dword v184, v[184:185], off nt
	s_and_b64 vcc, exec, s[4:5]
	s_waitcnt vmcnt(0)
	v_mul_f32_e32 v183, v183, v184
	ds_write_b32 v112, v183 offset:1056
	s_cbranch_vccnz .LBB0_123
	global_load_dword v113, v[86:87], off offset:32 nt
	s_waitcnt vmcnt(0)
	v_mul_f32_e32 v113, 0x3e0293ee, v113
.LBB0_123:
	v_lshl_add_u64 v[184:185], v[106:107], 0, s[56:57]
	global_load_dword v184, v[184:185], off nt
	v_mov_b32_e32 v183, 0x3e0293ee
	s_and_b64 vcc, exec, s[4:5]
	s_waitcnt vmcnt(0)
	v_mul_f32_e32 v113, v113, v184
	ds_write_b32 v112, v113 offset:1320
	v_mov_b32_e32 v113, 0x3e0293ee
	s_cbranch_vccnz .LBB0_125
	global_load_dword v113, v[86:87], off offset:40 nt
	s_waitcnt vmcnt(0)
	v_mul_f32_e32 v113, 0x3e0293ee, v113
.LBB0_125:
	v_lshl_add_u64 v[184:185], v[110:111], 0, s[56:57]
	global_load_dword v184, v[184:185], off nt
	s_and_b64 vcc, exec, s[4:5]
	s_waitcnt vmcnt(0)
	v_mul_f32_e32 v113, v113, v184
	ds_write_b32 v112, v113 offset:1584
	s_cbranch_vccnz .LBB0_127
	global_load_dword v113, v[86:87], off offset:48 nt
	s_waitcnt vmcnt(0)
	v_mul_f32_e32 v183, 0x3e0293ee, v113
.LBB0_127:
	v_lshl_add_u64 v[184:185], v[108:109], 0, s[56:57]
	global_load_dword v184, v[184:185], off nt
	v_mov_b32_e32 v113, 0x3e0293ee
	s_and_b64 vcc, exec, s[4:5]
	s_waitcnt vmcnt(0)
	v_mul_f32_e32 v183, v183, v184
	ds_write_b32 v112, v183 offset:1848
	v_mov_b32_e32 v183, 0x3e0293ee
	s_cbranch_vccnz .LBB0_129
	global_load_dword v183, v[86:87], off offset:56 nt
	s_waitcnt vmcnt(0)
	v_mul_f32_e32 v183, 0x3e0293ee, v183
.LBB0_129:
	v_lshl_add_u64 v[184:185], v[104:105], 0, s[56:57]
	global_load_dword v184, v[184:185], off nt
	s_and_b64 vcc, exec, s[4:5]
	s_waitcnt vmcnt(0)
	v_mul_f32_e32 v183, v183, v184
	ds_write_b32 v112, v183 offset:2112
	s_cbranch_vccnz .LBB0_131
	global_load_dword v113, v[86:87], off offset:64 nt
	s_waitcnt vmcnt(0)
	v_mul_f32_e32 v113, 0x3e0293ee, v113
.LBB0_131:
	v_lshl_add_u64 v[184:185], v[100:101], 0, s[56:57]
	global_load_dword v184, v[184:185], off nt
	v_mov_b32_e32 v183, 0x3e0293ee
	s_and_b64 vcc, exec, s[4:5]
	s_waitcnt vmcnt(0)
	v_mul_f32_e32 v113, v113, v184
	ds_write_b32 v112, v113 offset:2376
	v_mov_b32_e32 v113, 0x3e0293ee
	s_cbranch_vccnz .LBB0_133
	global_load_dword v113, v[86:87], off offset:72 nt
	s_waitcnt vmcnt(0)
	v_mul_f32_e32 v113, 0x3e0293ee, v113
.LBB0_133:
	v_lshl_add_u64 v[184:185], v[96:97], 0, s[56:57]
	global_load_dword v184, v[184:185], off nt
	s_and_b64 vcc, exec, s[4:5]
	s_waitcnt vmcnt(0)
	v_mul_f32_e32 v113, v113, v184
	ds_write_b32 v112, v113 offset:2640
	s_cbranch_vccnz .LBB0_135
	global_load_dword v113, v[86:87], off offset:80 nt
	s_waitcnt vmcnt(0)
	v_mul_f32_e32 v183, 0x3e0293ee, v113
.LBB0_135:
	v_lshl_add_u64 v[184:185], v[92:93], 0, s[56:57]
	global_load_dword v113, v[184:185], off nt
	v_mov_b32_e32 v184, 0x3e0293ee
	s_and_b64 vcc, exec, s[4:5]
	s_waitcnt vmcnt(0)
	v_mul_f32_e32 v113, v183, v113
	ds_write_b32 v112, v113 offset:2904
	v_mov_b32_e32 v113, 0x3e0293ee
	s_cbranch_vccnz .LBB0_137
	global_load_dword v113, v[86:87], off offset:88 nt
	s_waitcnt vmcnt(0)
	v_mul_f32_e32 v113, 0x3e0293ee, v113
.LBB0_137:
	v_lshl_add_u64 v[186:187], v[88:89], 0, s[56:57]
	global_load_dword v183, v[186:187], off nt
	s_and_b64 vcc, exec, s[4:5]
	s_waitcnt vmcnt(0)
	v_mul_f32_e32 v113, v113, v183
	ds_write_b32 v112, v113 offset:3168
	s_cbranch_vccnz .LBB0_139
	global_load_dword v113, v[86:87], off offset:96 nt
	s_waitcnt vmcnt(0)
	v_mul_f32_e32 v184, 0x3e0293ee, v113
.LBB0_139:
	v_lshl_add_u64 v[186:187], v[84:85], 0, s[56:57]
	global_load_dword v183, v[186:187], off nt
	v_mov_b32_e32 v113, 0x3e0293ee
	s_and_b64 vcc, exec, s[4:5]
	s_waitcnt vmcnt(0)
	v_mul_f32_e32 v183, v184, v183
	ds_write_b32 v112, v183 offset:3432
	v_mov_b32_e32 v183, 0x3e0293ee
	s_cbranch_vccnz .LBB0_141
	global_load_dword v183, v[86:87], off offset:104 nt
	s_waitcnt vmcnt(0)
	v_mul_f32_e32 v183, 0x3e0293ee, v183
.LBB0_141:
	v_lshl_add_u64 v[184:185], v[80:81], 0, s[56:57]
	global_load_dword v184, v[184:185], off nt
	s_and_b64 vcc, exec, s[4:5]
	s_waitcnt vmcnt(0)
	v_mul_f32_e32 v183, v183, v184
	ds_write_b32 v112, v183 offset:3696
	s_cbranch_vccnz .LBB0_110
	global_load_dword v113, v[86:87], off offset:112 nt
	s_waitcnt vmcnt(0)
	v_mul_f32_e32 v113, 0x3e0293ee, v113
	s_branch .LBB0_110

; __device__ __forceinline__ void tr_item(const float* W, int ldw, int K, int k0, int sc0, bf16* WT, int dr0, const float* gain, float cs, LAS float* scr, int lane) {
; #pragma unroll 16
;     for (int i = 0; i < 32; ++i) { const int kk = 2 * i + (lane >> 5); const float g = gain ? gain[k0 + kk] * cs : cs;
;         scr[kk * 33 + (lane & 31)] = W[(size_t)(k0 + kk) * ldw + sc0 + (lane & 31)] * g; }
.LBB0_145:
	s_andn2_b64 vcc, exec, s[4:5]
	s_cbranch_vccnz .LBB0_147
	s_lshl_b32 s4, s70, 1
	s_and_b32 s4, s4, 0x1fc0
	s_addk_i32 s4, 0xee00
	s_lshl_b32 s5, s70, 5
	s_and_b32 s56, s5, 0x3e0
	v_add_u32_e32 v80, s4, v2
	s_lshl_b32 s44, s56, 2
	v_add_u32_e32 v78, s4, v1
	v_ashrrev_i32_e32 v81, 31, v80
	v_add_u32_e32 v82, s4, v3
	v_add_u32_e32 v84, s4, v46
	v_add_u32_e32 v86, s4, v33
	v_add_u32_e32 v88, s4, v48
	v_add_u32_e32 v90, s4, v47
	v_add_u32_e32 v92, s4, v50
	v_lshl_add_u64 v[76:77], v[18:19], 0, s[44:45]
	v_ashrrev_i32_e32 v79, 31, v78
	v_lshlrev_b64 v[80:81], 12, v[80:81]
	v_ashrrev_i32_e32 v85, 31, v84
	v_ashrrev_i32_e32 v83, 31, v82
	v_ashrrev_i32_e32 v89, 31, v88
	v_ashrrev_i32_e32 v87, 31, v86
	v_ashrrev_i32_e32 v93, 31, v92
	v_ashrrev_i32_e32 v91, 31, v90
	v_lshlrev_b64 v[78:79], 12, v[78:79]
	v_lshl_add_u64 v[80:81], v[76:77], 0, v[80:81]
	v_lshlrev_b64 v[82:83], 12, v[82:83]
	v_lshlrev_b64 v[84:85], 12, v[84:85]
	v_lshlrev_b64 v[86:87], 12, v[86:87]
	v_lshlrev_b64 v[88:89], 12, v[88:89]
	v_lshlrev_b64 v[90:91], 12, v[90:91]
	v_lshlrev_b64 v[92:93], 12, v[92:93]
	v_lshl_add_u64 v[78:79], v[76:77], 0, v[78:79]
	v_lshl_add_u64 v[84:85], v[76:77], 0, v[84:85]
	v_lshl_add_u64 v[82:83], v[76:77], 0, v[82:83]
	v_lshl_add_u64 v[88:89], v[76:77], 0, v[88:89]
	v_lshl_add_u64 v[86:87], v[76:77], 0, v[86:87]
	v_lshl_add_u64 v[92:93], v[76:77], 0, v[92:93]
	v_lshl_add_u64 v[90:91], v[76:77], 0, v[90:91]
	global_load_dword v94, v[80:81], off nt
	global_load_dword v95, v[78:79], off nt
	global_load_dword v96, v[84:85], off nt
	global_load_dword v97, v[82:83], off nt
	global_load_dword v98, v[88:89], off nt
	global_load_dword v99, v[86:87], off nt
	global_load_dword v100, v[92:93], off nt
	global_load_dword v101, v[90:91], off nt
	v_add_u32_e32 v80, s4, v52
	v_add_u32_e32 v78, s4, v49
	v_ashrrev_i32_e32 v81, 31, v80
	v_add_u32_e32 v82, s4, v51
	v_add_u32_e32 v84, s4, v54
	v_add_u32_e32 v86, s4, v53
	v_add_u32_e32 v88, s4, v56
	v_add_u32_e32 v90, s4, v55
	v_add_u32_e32 v92, s4, v58
	v_ashrrev_i32_e32 v79, 31, v78
	v_lshlrev_b64 v[80:81], 12, v[80:81]
	v_ashrrev_i32_e32 v85, 31, v84
	v_ashrrev_i32_e32 v83, 31, v82
	v_ashrrev_i32_e32 v89, 31, v88
	v_ashrrev_i32_e32 v87, 31, v86
	v_ashrrev_i32_e32 v93, 31, v92
	v_ashrrev_i32_e32 v91, 31, v90
	v_lshlrev_b64 v[78:79], 12, v[78:79]
	v_lshl_add_u64 v[80:81], v[76:77], 0, v[80:81]
	v_lshlrev_b64 v[82:83], 12, v[82:83]
	v_lshlrev_b64 v[84:85], 12, v[84:85]
	v_lshlrev_b64 v[86:87], 12, v[86:87]
	v_lshlrev_b64 v[88:89], 12, v[88:89]
	v_lshlrev_b64 v[90:91], 12, v[90:91]
	v_lshlrev_b64 v[92:93], 12, v[92:93]
	v_lshl_add_u64 v[78:79], v[76:77], 0, v[78:79]
	v_lshl_add_u64 v[84:85], v[76:77], 0, v[84:85]
	v_lshl_add_u64 v[82:83], v[76:77], 0, v[82:83]
	v_lshl_add_u64 v[88:89], v[76:77], 0, v[88:89]
	v_lshl_add_u64 v[86:87], v[76:77], 0, v[86:87]
	v_lshl_add_u64 v[92:93], v[76:77], 0, v[92:93]
	v_lshl_add_u64 v[90:91], v[76:77], 0, v[90:91]
	global_load_dword v102, v[80:81], off nt
	global_load_dword v103, v[78:79], off nt
	global_load_dword v104, v[84:85], off nt
	global_load_dword v105, v[82:83], off nt
	global_load_dword v106, v[88:89], off nt
	global_load_dword v107, v[86:87], off nt
	global_load_dword v108, v[92:93], off nt
	global_load_dword v109, v[90:91], off nt
	v_add_u32_e32 v80, s4, v60
	v_add_u32_e32 v82, s4, v59
	v_add_u32_e32 v84, s4, v62
	v_add_u32_e32 v90, s4, v63
	v_add_u32_e32 v92, s4, v66
	v_add_u32_e32 v78, s4, v57
	v_ashrrev_i32_e32 v81, 31, v80
	v_ashrrev_i32_e32 v85, 31, v84
	v_ashrrev_i32_e32 v83, 31, v82
	v_add_u32_e32 v86, s4, v61
	v_add_u32_e32 v88, s4, v64
	v_ashrrev_i32_e32 v93, 31, v92
	v_ashrrev_i32_e32 v91, 31, v90
	v_ashrrev_i32_e32 v79, 31, v78
	v_lshlrev_b64 v[80:81], 12, v[80:81]
	v_lshlrev_b64 v[82:83], 12, v[82:83]
	v_lshlrev_b64 v[84:85], 12, v[84:85]
	v_ashrrev_i32_e32 v89, 31, v88
	v_ashrrev_i32_e32 v87, 31, v86
	v_lshlrev_b64 v[90:91], 12, v[90:91]
	v_lshlrev_b64 v[92:93], 12, v[92:93]
	v_lshlrev_b64 v[78:79], 12, v[78:79]
	v_lshl_add_u64 v[80:81], v[76:77], 0, v[80:81]
	v_lshl_add_u64 v[84:85], v[76:77], 0, v[84:85]
	v_lshl_add_u64 v[82:83], v[76:77], 0, v[82:83]
	v_lshlrev_b64 v[86:87], 12, v[86:87]
	v_lshlrev_b64 v[88:89], 12, v[88:89]
	v_lshl_add_u64 v[92:93], v[76:77], 0, v[92:93]
	v_lshl_add_u64 v[90:91], v[76:77], 0, v[90:91]
	v_lshl_add_u64 v[78:79], v[76:77], 0, v[78:79]
	v_lshl_add_u64 v[88:89], v[76:77], 0, v[88:89]
	v_lshl_add_u64 v[86:87], v[76:77], 0, v[86:87]
	global_load_dword v110, v[80:81], off nt
	global_load_dword v111, v[78:79], off nt
	global_load_dword v112, v[84:85], off nt
	global_load_dword v113, v[82:83], off nt
	global_load_dword v183, v[88:89], off nt
	global_load_dword v184, v[86:87], off nt
	s_nop 0
	global_load_dword v92, v[92:93], off nt
	s_nop 0
	global_load_dword v90, v[90:91], off nt
	v_add_u32_e32 v80, s4, v68
	v_add_u32_e32 v82, s4, v67
	v_add_u32_e32 v84, s4, v70
	v_add_u32_e32 v78, s4, v65
	v_ashrrev_i32_e32 v81, 31, v80
	v_ashrrev_i32_e32 v85, 31, v84
	v_ashrrev_i32_e32 v83, 31, v82
	v_add_u32_e32 v86, s4, v69
	v_add_u32_e32 v88, s4, v72
	v_ashrrev_i32_e32 v79, 31, v78
	v_lshlrev_b64 v[80:81], 12, v[80:81]
	v_lshlrev_b64 v[82:83], 12, v[82:83]
	v_lshlrev_b64 v[84:85], 12, v[84:85]
	v_ashrrev_i32_e32 v89, 31, v88
	v_ashrrev_i32_e32 v87, 31, v86
	v_lshlrev_b64 v[78:79], 12, v[78:79]
	v_lshl_add_u64 v[80:81], v[76:77], 0, v[80:81]
	v_lshl_add_u64 v[84:85], v[76:77], 0, v[84:85]
	v_lshl_add_u64 v[82:83], v[76:77], 0, v[82:83]
	v_lshlrev_b64 v[86:87], 12, v[86:87]
	v_lshlrev_b64 v[88:89], 12, v[88:89]
	v_lshl_add_u64 v[78:79], v[76:77], 0, v[78:79]
	v_lshl_add_u64 v[88:89], v[76:77], 0, v[88:89]
	v_lshl_add_u64 v[86:87], v[76:77], 0, v[86:87]
	global_load_dword v91, v[80:81], off nt
	global_load_dword v93, v[78:79], off nt
	s_nop 0
	global_load_dword v84, v[84:85], off nt
	s_nop 0
	global_load_dword v82, v[82:83], off nt
	s_nop 0
	global_load_dword v83, v[88:89], off nt
	global_load_dword v85, v[86:87], off nt
	v_add_u32_e32 v80, s4, v74
	v_add_u32_e32 v78, s4, v71
	v_ashrrev_i32_e32 v81, 31, v80
	v_ashrrev_i32_e32 v79, 31, v78
	v_lshlrev_b64 v[80:81], 12, v[80:81]
	v_lshlrev_b64 v[78:79], 12, v[78:79]
	v_lshl_add_u64 v[80:81], v[76:77], 0, v[80:81]
	global_load_dword v80, v[80:81], off nt
	v_lshl_add_u64 v[76:77], v[76:77], 0, v[78:79]
	global_load_dword v76, v[76:77], off nt
	v_add_u32_e32 v77, v73, v118
	s_waitcnt vmcnt(31)
; #define LAS __attribute__((address_space(3)))
; __device__ __forceinline__ unsigned pk2(float lo, float hi) { return pg8::cvt_pk_bf16(lo, hi); }
; __device__ __forceinline__ void tr_item(const float* W, int ldw, int K, int k0, int sc0, bf16* WT, int dr0, const float* gain, float cs, LAS float* scr, int lane) {
;     ...
;         scr[kk * 33 + (lane & 31)] = W[(size_t)(k0 + kk) * ldw + sc0 + (lane & 31)] * g; }
;     asm volatile("s_waitcnt lgkmcnt(0)" ::: "memory");
;     const int c = lane & 7;
; #pragma unroll
;     for (int j = 0; j < 4; ++j) { const int n = (lane >> 3) + 8 * j; const LAS float* s = scr + (8 * c) * 33 + n;
;         u32x4 o; o.x = pk2(s[0 * 33], s[1 * 33]); o.y = pk2(s[2 * 33], s[3 * 33]); o.z = pk2(s[4 * 33], s[5 * 33]); o.w = pk2(s[6 * 33], s[7 * 33]);
;         *(u32x4*)(WT + (size_t)(dr0 + n) * K + k0 + 8 * c) = o; }
	ds_write_b32 v77, v94
	v_add_u32_e32 v77, v73, v119
	s_waitcnt vmcnt(30)
	ds_write_b32 v77, v95
	v_add_u32_e32 v77, v73, v120
	s_waitcnt vmcnt(29)
	ds_write_b32 v77, v96
	v_add_u32_e32 v77, v73, v121
	s_waitcnt vmcnt(28)
	ds_write_b32 v77, v97
	v_add_u32_e32 v77, v73, v122
	s_waitcnt vmcnt(27)
	ds_write_b32 v77, v98
	v_add_u32_e32 v77, v73, v123
	s_waitcnt vmcnt(26)
	ds_write_b32 v77, v99
	v_add_u32_e32 v77, v73, v124
	s_waitcnt vmcnt(25)
	ds_write_b32 v77, v100
	v_add_u32_e32 v77, v73, v126
	s_waitcnt vmcnt(24)
	ds_write_b32 v77, v101
	v_add_u32_e32 v77, v73, v127
	s_waitcnt vmcnt(23)
	ds_write_b32 v77, v102
	v_add_u32_e32 v77, v73, v128
	s_waitcnt vmcnt(22)
	ds_write_b32 v77, v103
	v_add_u32_e32 v77, v73, v129
	s_waitcnt vmcnt(21)
	ds_write_b32 v77, v104
	v_add_u32_e32 v77, v73, v130
	s_waitcnt vmcnt(20)
	ds_write_b32 v77, v105
	v_add_u32_e32 v77, v73, v131
	s_waitcnt vmcnt(19)
	ds_write_b32 v77, v106
	v_add_u32_e32 v77, v73, v132
	s_waitcnt vmcnt(18)
	ds_write_b32 v77, v107
	v_add_u32_e32 v77, v73, v133
	s_waitcnt vmcnt(17)
	ds_write_b32 v77, v108
	v_add_u32_e32 v77, v73, v134
	s_waitcnt vmcnt(16)
	ds_write_b32 v77, v109
	v_add_u32_e32 v77, v73, v135
	s_mov_b32 s5, s45
	s_waitcnt vmcnt(15)
	ds_write_b32 v77, v110
	v_add_u32_e32 v77, v73, v136
	s_waitcnt vmcnt(14)
	ds_write_b32 v77, v111
	v_add_u32_e32 v77, v73, v137
	s_waitcnt vmcnt(13)
	ds_write_b32 v77, v112
	v_add_u32_e32 v77, v73, v138
	s_waitcnt vmcnt(12)
	ds_write_b32 v77, v113
	v_add_u32_e32 v77, v73, v139
	s_waitcnt vmcnt(11)
	ds_write_b32 v77, v183
	v_add_u32_e32 v77, v73, v140
	s_waitcnt vmcnt(10)
	ds_write_b32 v77, v184
	v_add_u32_e32 v77, v73, v141
	s_waitcnt vmcnt(9)
	ds_write_b32 v77, v92
	v_add_u32_e32 v77, v73, v142
	s_waitcnt vmcnt(8)
	ds_write_b32 v77, v90
	v_add_u32_e32 v77, v73, v143
	s_waitcnt vmcnt(7)
	ds_write_b32 v77, v91
	v_add_u32_e32 v77, v73, v144
	s_waitcnt vmcnt(6)
	ds_write_b32 v77, v93
	v_add_u32_e32 v77, v73, v145
	s_waitcnt vmcnt(5)
	ds_write_b32 v77, v84
	v_add_u32_e32 v77, v73, v146
	s_waitcnt vmcnt(4)
	ds_write_b32 v77, v82
	v_add_u32_e32 v77, v73, v147
	s_waitcnt vmcnt(3)
	ds_write_b32 v77, v83
	v_add_u32_e32 v77, v73, v148
	s_waitcnt vmcnt(2)
	ds_write_b32 v77, v85
	v_add_u32_e32 v77, v73, v149
	v_lshl_add_u64 v[82:83], s[4:5], 1, v[20:21]
	s_waitcnt vmcnt(1)
	ds_write_b32 v77, v80
	v_add_u32_e32 v77, v73, v150
	s_waitcnt vmcnt(0)
	ds_write_b32 v77, v76
	s_waitcnt lgkmcnt(0)
	ds_read2_b32 v[76:77], v75 offset1:33
	s_waitcnt lgkmcnt(0)
	v_cvt_pk_bf16_f32 v76, v76, v77
	ds_read2_b32 v[78:79], v75 offset0:66 offset1:99
	s_waitcnt lgkmcnt(0)
	v_cvt_pk_bf16_f32 v77, v78, v79
	ds_read2_b32 v[78:79], v75 offset0:132 offset1:165
	s_waitcnt lgkmcnt(0)
	v_cvt_pk_bf16_f32 v78, v78, v79
	ds_read2_b32 v[80:81], v75 offset0:198 offset1:231
	s_waitcnt lgkmcnt(0)
	v_cvt_pk_bf16_f32 v79, v80, v81
	v_add_u32_e32 v80, s56, v0
	v_ashrrev_i32_e32 v81, 31, v80
	v_lshlrev_b64 v[80:81], 11, v[80:81]
	v_lshl_add_u64 v[80:81], v[82:83], 0, v[80:81]
	ds_read2_b32 v[84:85], v75 offset0:8 offset1:41
	global_store_dwordx4 v[80:81], v[76:79], off
	s_waitcnt lgkmcnt(0)
	s_nop 0
	v_cvt_pk_bf16_f32 v76, v84, v85
	ds_read2_b32 v[78:79], v75 offset0:74 offset1:107
	s_waitcnt lgkmcnt(0)
	v_cvt_pk_bf16_f32 v77, v78, v79
	ds_read2_b32 v[78:79], v75 offset0:140 offset1:173
	s_waitcnt lgkmcnt(0)
	v_cvt_pk_bf16_f32 v78, v78, v79
	ds_read2_b32 v[80:81], v75 offset0:206 offset1:239
	s_waitcnt lgkmcnt(0)
	v_cvt_pk_bf16_f32 v79, v80, v81
	v_add_u32_e32 v80, s56, v114
	v_ashrrev_i32_e32 v81, 31, v80
	v_lshlrev_b64 v[80:81], 11, v[80:81]
	v_lshl_add_u64 v[80:81], v[82:83], 0, v[80:81]
	ds_read2_b32 v[84:85], v75 offset0:16 offset1:49
	global_store_dwordx4 v[80:81], v[76:79], off
	s_waitcnt lgkmcnt(0)
	s_nop 0
	v_cvt_pk_bf16_f32 v76, v84, v85
	ds_read2_b32 v[78:79], v75 offset0:82 offset1:115
	s_waitcnt lgkmcnt(0)
	v_cvt_pk_bf16_f32 v77, v78, v79
	ds_read2_b32 v[78:79], v75 offset0:148 offset1:181
	s_waitcnt lgkmcnt(0)
	v_cvt_pk_bf16_f32 v78, v78, v79
	ds_read2_b32 v[80:81], v75 offset0:214 offset1:247
	s_waitcnt lgkmcnt(0)
	v_cvt_pk_bf16_f32 v79, v80, v81
	v_add_u32_e32 v80, s56, v115
	v_ashrrev_i32_e32 v81, 31, v80
	v_lshlrev_b64 v[80:81], 11, v[80:81]
	v_lshl_add_u64 v[80:81], v[82:83], 0, v[80:81]
	ds_read2_b32 v[84:85], v75 offset0:24 offset1:57
	global_store_dwordx4 v[80:81], v[76:79], off
	s_waitcnt lgkmcnt(0)
	s_nop 0
	v_cvt_pk_bf16_f32 v76, v84, v85
	ds_read2_b32 v[78:79], v75 offset0:90 offset1:123
	s_waitcnt lgkmcnt(0)
	v_cvt_pk_bf16_f32 v77, v78, v79
	ds_read2_b32 v[78:79], v75 offset0:156 offset1:189
	s_waitcnt lgkmcnt(0)
	v_cvt_pk_bf16_f32 v78, v78, v79
	ds_read2_b32 v[80:81], v75 offset0:222 offset1:255
	s_waitcnt lgkmcnt(0)
	v_cvt_pk_bf16_f32 v79, v80, v81
	v_add_u32_e32 v80, s56, v116
	v_ashrrev_i32_e32 v81, 31, v80
	v_lshlrev_b64 v[80:81], 11, v[80:81]
	v_lshl_add_u64 v[80:81], v[82:83], 0, v[80:81]
	global_store_dwordx4 v[80:81], v[76:79], off
	s_waitcnt lgkmcnt(0)

; __device__ __forceinline__ void tr_item(const float* W, int ldw, int K, int k0, int sc0, bf16* WT, int dr0, const float* gain, float cs, LAS float* scr, int lane) {
; #pragma unroll 16
;     for (int i = 0; i < 32; ++i) { const int kk = 2 * i + (lane >> 5); const float g = gain ? gain[k0 + kk] * cs : cs;
;         scr[kk * 33 + (lane & 31)] = W[(size_t)(k0 + kk) * ldw + sc0 + (lane & 31)] * g; }
.LBB0_148:
	s_andn2_b64 vcc, exec, s[4:5]
	s_cbranch_vccnz .LBB0_150
	s_lshl_b32 s4, s70, 1
	s_and_b32 s4, s4, 0x1fc0
	s_addk_i32 s4, 0xf000
	s_lshl_b32 s5, s70, 5
	s_and_b32 s56, s5, 0x3e0
	v_add_u32_e32 v80, s4, v2
	s_lshl_b32 s44, s56, 2
	v_add_u32_e32 v78, s4, v1
	v_ashrrev_i32_e32 v81, 31, v80
	v_add_u32_e32 v82, s4, v3
	v_add_u32_e32 v84, s4, v46
	v_add_u32_e32 v86, s4, v33
	v_add_u32_e32 v88, s4, v48
	v_add_u32_e32 v90, s4, v47
	v_add_u32_e32 v92, s4, v50
	v_lshl_add_u64 v[76:77], v[22:23], 0, s[44:45]
	v_ashrrev_i32_e32 v79, 31, v78
	v_lshlrev_b64 v[80:81], 12, v[80:81]
	v_ashrrev_i32_e32 v85, 31, v84
	v_ashrrev_i32_e32 v83, 31, v82
	v_ashrrev_i32_e32 v89, 31, v88
	v_ashrrev_i32_e32 v87, 31, v86
	v_ashrrev_i32_e32 v93, 31, v92
	v_ashrrev_i32_e32 v91, 31, v90
	v_lshlrev_b64 v[78:79], 12, v[78:79]
	v_lshl_add_u64 v[80:81], v[76:77], 0, v[80:81]
	v_lshlrev_b64 v[82:83], 12, v[82:83]
	v_lshlrev_b64 v[84:85], 12, v[84:85]
	v_lshlrev_b64 v[86:87], 12, v[86:87]
	v_lshlrev_b64 v[88:89], 12, v[88:89]
	v_lshlrev_b64 v[90:91], 12, v[90:91]
	v_lshlrev_b64 v[92:93], 12, v[92:93]
	v_lshl_add_u64 v[78:79], v[76:77], 0, v[78:79]
	v_lshl_add_u64 v[84:85], v[76:77], 0, v[84:85]
	v_lshl_add_u64 v[82:83], v[76:77], 0, v[82:83]
	v_lshl_add_u64 v[88:89], v[76:77], 0, v[88:89]
	v_lshl_add_u64 v[86:87], v[76:77], 0, v[86:87]
	v_lshl_add_u64 v[92:93], v[76:77], 0, v[92:93]
	v_lshl_add_u64 v[90:91], v[76:77], 0, v[90:91]
	global_load_dword v94, v[80:81], off nt
	global_load_dword v95, v[78:79], off nt
	global_load_dword v96, v[84:85], off nt
	global_load_dword v97, v[82:83], off nt
	global_load_dword v98, v[88:89], off nt
	global_load_dword v99, v[86:87], off nt
	global_load_dword v100, v[92:93], off nt
	global_load_dword v101, v[90:91], off nt
	v_add_u32_e32 v80, s4, v52
	v_add_u32_e32 v78, s4, v49
	v_ashrrev_i32_e32 v81, 31, v80
	v_add_u32_e32 v82, s4, v51
	v_add_u32_e32 v84, s4, v54
	v_add_u32_e32 v86, s4, v53
	v_add_u32_e32 v88, s4, v56
	v_add_u32_e32 v90, s4, v55
	v_add_u32_e32 v92, s4, v58
	v_ashrrev_i32_e32 v79, 31, v78
	v_lshlrev_b64 v[80:81], 12, v[80:81]
	v_ashrrev_i32_e32 v85, 31, v84
	v_ashrrev_i32_e32 v83, 31, v82
	v_ashrrev_i32_e32 v89, 31, v88
	v_ashrrev_i32_e32 v87, 31, v86
	v_ashrrev_i32_e32 v93, 31, v92
	v_ashrrev_i32_e32 v91, 31, v90
	v_lshlrev_b64 v[78:79], 12, v[78:79]
	v_lshl_add_u64 v[80:81], v[76:77], 0, v[80:81]
	v_lshlrev_b64 v[82:83], 12, v[82:83]
	v_lshlrev_b64 v[84:85], 12, v[84:85]
	v_lshlrev_b64 v[86:87], 12, v[86:87]
	v_lshlrev_b64 v[88:89], 12, v[88:89]
	v_lshlrev_b64 v[90:91], 12, v[90:91]
	v_lshlrev_b64 v[92:93], 12, v[92:93]
	v_lshl_add_u64 v[78:79], v[76:77], 0, v[78:79]
	v_lshl_add_u64 v[84:85], v[76:77], 0, v[84:85]
	v_lshl_add_u64 v[82:83], v[76:77], 0, v[82:83]
	v_lshl_add_u64 v[88:89], v[76:77], 0, v[88:89]
	v_lshl_add_u64 v[86:87], v[76:77], 0, v[86:87]
	v_lshl_add_u64 v[92:93], v[76:77], 0, v[92:93]
	v_lshl_add_u64 v[90:91], v[76:77], 0, v[90:91]
	global_load_dword v102, v[80:81], off nt
	global_load_dword v103, v[78:79], off nt
	global_load_dword v104, v[84:85], off nt
	global_load_dword v105, v[82:83], off nt
	global_load_dword v106, v[88:89], off nt
	global_load_dword v107, v[86:87], off nt
	global_load_dword v108, v[92:93], off nt
	global_load_dword v109, v[90:91], off nt
	v_add_u32_e32 v80, s4, v60
	v_add_u32_e32 v82, s4, v59
	v_add_u32_e32 v84, s4, v62
	v_add_u32_e32 v90, s4, v63
	v_add_u32_e32 v92, s4, v66
	v_add_u32_e32 v78, s4, v57
	v_ashrrev_i32_e32 v81, 31, v80
	v_ashrrev_i32_e32 v85, 31, v84
	v_ashrrev_i32_e32 v83, 31, v82
	v_add_u32_e32 v86, s4, v61
	v_add_u32_e32 v88, s4, v64
	v_ashrrev_i32_e32 v93, 31, v92
	v_ashrrev_i32_e32 v91, 31, v90
	v_ashrrev_i32_e32 v79, 31, v78
	v_lshlrev_b64 v[80:81], 12, v[80:81]
	v_lshlrev_b64 v[82:83], 12, v[82:83]
	v_lshlrev_b64 v[84:85], 12, v[84:85]
	v_ashrrev_i32_e32 v89, 31, v88
	v_ashrrev_i32_e32 v87, 31, v86
	v_lshlrev_b64 v[90:91], 12, v[90:91]
	v_lshlrev_b64 v[92:93], 12, v[92:93]
	v_lshlrev_b64 v[78:79], 12, v[78:79]
	v_lshl_add_u64 v[80:81], v[76:77], 0, v[80:81]
	v_lshl_add_u64 v[84:85], v[76:77], 0, v[84:85]
	v_lshl_add_u64 v[82:83], v[76:77], 0, v[82:83]
	v_lshlrev_b64 v[86:87], 12, v[86:87]
	v_lshlrev_b64 v[88:89], 12, v[88:89]
	v_lshl_add_u64 v[92:93], v[76:77], 0, v[92:93]
	v_lshl_add_u64 v[90:91], v[76:77], 0, v[90:91]
	v_lshl_add_u64 v[78:79], v[76:77], 0, v[78:79]
	v_lshl_add_u64 v[88:89], v[76:77], 0, v[88:89]
	v_lshl_add_u64 v[86:87], v[76:77], 0, v[86:87]
	global_load_dword v110, v[80:81], off nt
	global_load_dword v111, v[78:79], off nt
	global_load_dword v112, v[84:85], off nt
	global_load_dword v113, v[82:83], off nt
	global_load_dword v183, v[88:89], off nt
	global_load_dword v184, v[86:87], off nt
	s_nop 0
	global_load_dword v92, v[92:93], off nt
	s_nop 0
	global_load_dword v90, v[90:91], off nt
	v_add_u32_e32 v80, s4, v68
	v_add_u32_e32 v82, s4, v67
	v_add_u32_e32 v84, s4, v70
	v_add_u32_e32 v78, s4, v65
	v_ashrrev_i32_e32 v81, 31, v80
	v_ashrrev_i32_e32 v85, 31, v84
	v_ashrrev_i32_e32 v83, 31, v82
	v_add_u32_e32 v86, s4, v69
	v_add_u32_e32 v88, s4, v72
	v_ashrrev_i32_e32 v79, 31, v78
	v_lshlrev_b64 v[80:81], 12, v[80:81]
	v_lshlrev_b64 v[82:83], 12, v[82:83]
	v_lshlrev_b64 v[84:85], 12, v[84:85]
	v_ashrrev_i32_e32 v89, 31, v88
	v_ashrrev_i32_e32 v87, 31, v86
	v_lshlrev_b64 v[78:79], 12, v[78:79]
	v_lshl_add_u64 v[80:81], v[76:77], 0, v[80:81]
	v_lshl_add_u64 v[84:85], v[76:77], 0, v[84:85]
	v_lshl_add_u64 v[82:83], v[76:77], 0, v[82:83]
	v_lshlrev_b64 v[86:87], 12, v[86:87]
	v_lshlrev_b64 v[88:89], 12, v[88:89]
	v_lshl_add_u64 v[78:79], v[76:77], 0, v[78:79]
	v_lshl_add_u64 v[88:89], v[76:77], 0, v[88:89]
	v_lshl_add_u64 v[86:87], v[76:77], 0, v[86:87]
	global_load_dword v91, v[80:81], off nt
	global_load_dword v93, v[78:79], off nt
	s_nop 0
	global_load_dword v84, v[84:85], off nt
	s_nop 0
	global_load_dword v82, v[82:83], off nt
	s_nop 0
	global_load_dword v83, v[88:89], off nt
	global_load_dword v85, v[86:87], off nt
	v_add_u32_e32 v80, s4, v74
	v_add_u32_e32 v78, s4, v71
	v_ashrrev_i32_e32 v81, 31, v80
	v_ashrrev_i32_e32 v79, 31, v78
	v_lshlrev_b64 v[80:81], 12, v[80:81]
	v_lshlrev_b64 v[78:79], 12, v[78:79]
	v_lshl_add_u64 v[80:81], v[76:77], 0, v[80:81]
	global_load_dword v80, v[80:81], off nt
	v_lshl_add_u64 v[76:77], v[76:77], 0, v[78:79]
	global_load_dword v76, v[76:77], off nt
	v_add_u32_e32 v77, v73, v118
	s_waitcnt vmcnt(31)
; #define LAS __attribute__((address_space(3)))
; __device__ __forceinline__ unsigned pk2(float lo, float hi) { return pg8::cvt_pk_bf16(lo, hi); }
; __device__ __forceinline__ void tr_item(const float* W, int ldw, int K, int k0, int sc0, bf16* WT, int dr0, const float* gain, float cs, LAS float* scr, int lane) {
;     ...
;         scr[kk * 33 + (lane & 31)] = W[(size_t)(k0 + kk) * ldw + sc0 + (lane & 31)] * g; }
;     asm volatile("s_waitcnt lgkmcnt(0)" ::: "memory");
;     const int c = lane & 7;
; #pragma unroll
;     for (int j = 0; j < 4; ++j) { const int n = (lane >> 3) + 8 * j; const LAS float* s = scr + (8 * c) * 33 + n;
;         u32x4 o; o.x = pk2(s[0 * 33], s[1 * 33]); o.y = pk2(s[2 * 33], s[3 * 33]); o.z = pk2(s[4 * 33], s[5 * 33]); o.w = pk2(s[6 * 33], s[7 * 33]);
;         *(u32x4*)(WT + (size_t)(dr0 + n) * K + k0 + 8 * c) = o; }
	ds_write_b32 v77, v94
	v_add_u32_e32 v77, v73, v119
	s_waitcnt vmcnt(30)
	ds_write_b32 v77, v95
	v_add_u32_e32 v77, v73, v120
	s_waitcnt vmcnt(29)
	ds_write_b32 v77, v96
	v_add_u32_e32 v77, v73, v121
	s_waitcnt vmcnt(28)
	ds_write_b32 v77, v97
	v_add_u32_e32 v77, v73, v122
	s_waitcnt vmcnt(27)
	ds_write_b32 v77, v98
	v_add_u32_e32 v77, v73, v123
	s_waitcnt vmcnt(26)
	ds_write_b32 v77, v99
	v_add_u32_e32 v77, v73, v124
	s_waitcnt vmcnt(25)
	ds_write_b32 v77, v100
	v_add_u32_e32 v77, v73, v126
	s_waitcnt vmcnt(24)
	ds_write_b32 v77, v101
	v_add_u32_e32 v77, v73, v127
	s_waitcnt vmcnt(23)
	ds_write_b32 v77, v102
	v_add_u32_e32 v77, v73, v128
	s_waitcnt vmcnt(22)
	ds_write_b32 v77, v103
	v_add_u32_e32 v77, v73, v129
	s_waitcnt vmcnt(21)
	ds_write_b32 v77, v104
	v_add_u32_e32 v77, v73, v130
	s_waitcnt vmcnt(20)
	ds_write_b32 v77, v105
	v_add_u32_e32 v77, v73, v131
	s_waitcnt vmcnt(19)
	ds_write_b32 v77, v106
	v_add_u32_e32 v77, v73, v132
	s_waitcnt vmcnt(18)
	ds_write_b32 v77, v107
	v_add_u32_e32 v77, v73, v133
	s_waitcnt vmcnt(17)
	ds_write_b32 v77, v108
	v_add_u32_e32 v77, v73, v134
	s_waitcnt vmcnt(16)
	ds_write_b32 v77, v109
	v_add_u32_e32 v77, v73, v135
	s_mov_b32 s5, s45
	s_waitcnt vmcnt(15)
	ds_write_b32 v77, v110
	v_add_u32_e32 v77, v73, v136
	s_waitcnt vmcnt(14)
	ds_write_b32 v77, v111
	v_add_u32_e32 v77, v73, v137
	s_waitcnt vmcnt(13)
	ds_write_b32 v77, v112
	v_add_u32_e32 v77, v73, v138
	s_waitcnt vmcnt(12)
	ds_write_b32 v77, v113
	v_add_u32_e32 v77, v73, v139
	s_waitcnt vmcnt(11)
	ds_write_b32 v77, v183
	v_add_u32_e32 v77, v73, v140
	s_waitcnt vmcnt(10)
	ds_write_b32 v77, v184
	v_add_u32_e32 v77, v73, v141
	s_waitcnt vmcnt(9)
	ds_write_b32 v77, v92
	v_add_u32_e32 v77, v73, v142
	s_waitcnt vmcnt(8)
	ds_write_b32 v77, v90
	v_add_u32_e32 v77, v73, v143
	s_waitcnt vmcnt(7)
	ds_write_b32 v77, v91
	v_add_u32_e32 v77, v73, v144
	s_waitcnt vmcnt(6)
	ds_write_b32 v77, v93
	v_add_u32_e32 v77, v73, v145
	s_waitcnt vmcnt(5)
	ds_write_b32 v77, v84
	v_add_u32_e32 v77, v73, v146
	s_waitcnt vmcnt(4)
	ds_write_b32 v77, v82
	v_add_u32_e32 v77, v73, v147
	s_waitcnt vmcnt(3)
	ds_write_b32 v77, v83
	v_add_u32_e32 v77, v73, v148
	s_waitcnt vmcnt(2)
	ds_write_b32 v77, v85
	v_add_u32_e32 v77, v73, v149
	v_lshl_add_u64 v[82:83], s[4:5], 1, v[24:25]
	s_waitcnt vmcnt(1)
	ds_write_b32 v77, v80
	v_add_u32_e32 v77, v73, v150
	s_waitcnt vmcnt(0)
	ds_write_b32 v77, v76
	s_waitcnt lgkmcnt(0)
	ds_read2_b32 v[76:77], v75 offset1:33
	s_waitcnt lgkmcnt(0)
	v_cvt_pk_bf16_f32 v76, v76, v77
	ds_read2_b32 v[78:79], v75 offset0:66 offset1:99
	s_waitcnt lgkmcnt(0)
	v_cvt_pk_bf16_f32 v77, v78, v79
	ds_read2_b32 v[78:79], v75 offset0:132 offset1:165
	s_waitcnt lgkmcnt(0)
	v_cvt_pk_bf16_f32 v78, v78, v79
	ds_read2_b32 v[80:81], v75 offset0:198 offset1:231
	s_waitcnt lgkmcnt(0)
	v_cvt_pk_bf16_f32 v79, v80, v81
	v_add_u32_e32 v80, s56, v0
	v_ashrrev_i32_e32 v81, 31, v80
	v_lshlrev_b64 v[80:81], 11, v[80:81]
	v_lshl_add_u64 v[80:81], v[82:83], 0, v[80:81]
	ds_read2_b32 v[84:85], v75 offset0:8 offset1:41
	global_store_dwordx4 v[80:81], v[76:79], off
	s_waitcnt lgkmcnt(0)
	s_nop 0
	v_cvt_pk_bf16_f32 v76, v84, v85
	ds_read2_b32 v[78:79], v75 offset0:74 offset1:107
	s_waitcnt lgkmcnt(0)
	v_cvt_pk_bf16_f32 v77, v78, v79
	ds_read2_b32 v[78:79], v75 offset0:140 offset1:173
	s_waitcnt lgkmcnt(0)
	v_cvt_pk_bf16_f32 v78, v78, v79
	ds_read2_b32 v[80:81], v75 offset0:206 offset1:239
	s_waitcnt lgkmcnt(0)
	v_cvt_pk_bf16_f32 v79, v80, v81
	v_add_u32_e32 v80, s56, v114
	v_ashrrev_i32_e32 v81, 31, v80
	v_lshlrev_b64 v[80:81], 11, v[80:81]
	v_lshl_add_u64 v[80:81], v[82:83], 0, v[80:81]
	ds_read2_b32 v[84:85], v75 offset0:16 offset1:49
	global_store_dwordx4 v[80:81], v[76:79], off
	s_waitcnt lgkmcnt(0)
	s_nop 0
	v_cvt_pk_bf16_f32 v76, v84, v85
	ds_read2_b32 v[78:79], v75 offset0:82 offset1:115
	s_waitcnt lgkmcnt(0)
	v_cvt_pk_bf16_f32 v77, v78, v79
	ds_read2_b32 v[78:79], v75 offset0:148 offset1:181
	s_waitcnt lgkmcnt(0)
	v_cvt_pk_bf16_f32 v78, v78, v79
	ds_read2_b32 v[80:81], v75 offset0:214 offset1:247
	s_waitcnt lgkmcnt(0)
	v_cvt_pk_bf16_f32 v79, v80, v81
	v_add_u32_e32 v80, s56, v115
	v_ashrrev_i32_e32 v81, 31, v80
	v_lshlrev_b64 v[80:81], 11, v[80:81]
	v_lshl_add_u64 v[80:81], v[82:83], 0, v[80:81]
	ds_read2_b32 v[84:85], v75 offset0:24 offset1:57
	global_store_dwordx4 v[80:81], v[76:79], off
	s_waitcnt lgkmcnt(0)
	s_nop 0
	v_cvt_pk_bf16_f32 v76, v84, v85
	ds_read2_b32 v[78:79], v75 offset0:90 offset1:123
	s_waitcnt lgkmcnt(0)
	v_cvt_pk_bf16_f32 v77, v78, v79
	ds_read2_b32 v[78:79], v75 offset0:156 offset1:189
	s_waitcnt lgkmcnt(0)
	v_cvt_pk_bf16_f32 v78, v78, v79
	ds_read2_b32 v[80:81], v75 offset0:222 offset1:255
	s_waitcnt lgkmcnt(0)
	v_cvt_pk_bf16_f32 v79, v80, v81
	v_add_u32_e32 v80, s56, v116
	v_ashrrev_i32_e32 v81, 31, v80
	v_lshlrev_b64 v[80:81], 11, v[80:81]
	v_lshl_add_u64 v[80:81], v[82:83], 0, v[80:81]
	global_store_dwordx4 v[80:81], v[76:79], off
	s_waitcnt lgkmcnt(0)

; __device__ __forceinline__ void tr_item(const float* W, int ldw, int K, int k0, int sc0, bf16* WT, int dr0, const float* gain, float cs, LAS float* scr, int lane) {
; #pragma unroll 16
;     for (int i = 0; i < 32; ++i) { const int kk = 2 * i + (lane >> 5); const float g = gain ? gain[k0 + kk] * cs : cs;
;         scr[kk * 33 + (lane & 31)] = W[(size_t)(k0 + kk) * ldw + sc0 + (lane & 31)] * g; }
.LBB0_153:
	v_lshl_add_u64 v[112:113], v[76:77], 0, s[58:59]
	global_load_dword v112, v[112:113], off nt
	s_add_u32 s58, s58, 0x80400
	s_addc_u32 s59, s59, 0
	s_add_u32 s60, s60, 0x80
	s_addc_u32 s61, s61, 0
	s_cmp_lg_u32 s58, 0x100800
	s_waitcnt vmcnt(0)
	v_mul_f32_e32 v112, v184, v112
	ds_write_b32 v183, v112 offset:3960
	v_add_u32_e32 v183, 0x1080, v183
	s_cbranch_scc0 .LBB0_16
.LBB0_154:
	v_cndmask_b32_e64 v112, 0, 1, s[52:53]
	v_mov_b32_e32 v184, 1.0
	v_cmp_ne_u32_e64 s[4:5], 1, v112
	s_andn2_b64 vcc, exec, s[52:53]
	v_mov_b32_e32 v112, 1.0
	s_cbranch_vccnz .LBB0_156
	v_lshl_add_u64 v[112:113], s[60:61], 0, v[110:111]
	global_load_dword v112, v[112:113], off nt
.LBB0_156:
	v_lshl_add_u64 v[186:187], v[108:109], 0, s[58:59]
	global_load_dword v113, v[186:187], off nt
	s_and_b64 vcc, exec, s[4:5]
	s_waitcnt vmcnt(0)
	v_mul_f32_e32 v112, v112, v113
	ds_write_b32 v183, v112
	v_lshl_add_u64 v[112:113], s[60:61], 0, v[78:79]
	s_cbranch_vccnz .LBB0_158
	global_load_dword v184, v[112:113], off offset:8 nt
.LBB0_158:
	v_lshl_add_u64 v[186:187], v[106:107], 0, s[58:59]
	global_load_dword v186, v[186:187], off nt
	v_mov_b32_e32 v185, 1.0
	s_and_b64 vcc, exec, s[4:5]
	s_waitcnt vmcnt(0)
	v_mul_f32_e32 v184, v184, v186
	ds_write_b32 v183, v184 offset:264
	v_mov_b32_e32 v184, 1.0
	s_cbranch_vccnz .LBB0_160
	global_load_dword v184, v[112:113], off offset:16 nt
.LBB0_160:
	v_lshl_add_u64 v[186:187], v[104:105], 0, s[58:59]
	global_load_dword v186, v[186:187], off nt
	s_and_b64 vcc, exec, s[4:5]
	s_waitcnt vmcnt(0)
	v_mul_f32_e32 v184, v184, v186
	ds_write_b32 v183, v184 offset:528
	s_cbranch_vccnz .LBB0_162
	global_load_dword v185, v[112:113], off offset:24 nt
.LBB0_162:
	v_lshl_add_u64 v[186:187], v[102:103], 0, s[58:59]
	global_load_dword v186, v[186:187], off nt
	v_mov_b32_e32 v184, 1.0
	s_and_b64 vcc, exec, s[4:5]
	s_waitcnt vmcnt(0)
	v_mul_f32_e32 v185, v185, v186
	ds_write_b32 v183, v185 offset:792
	v_mov_b32_e32 v185, 1.0
	s_cbranch_vccnz .LBB0_164
	global_load_dword v185, v[112:113], off offset:32 nt
.LBB0_164:
	v_lshl_add_u64 v[186:187], v[100:101], 0, s[58:59]
	global_load_dword v186, v[186:187], off nt
	s_and_b64 vcc, exec, s[4:5]
	s_waitcnt vmcnt(0)
	v_mul_f32_e32 v185, v185, v186
	ds_write_b32 v183, v185 offset:1056
	s_cbranch_vccnz .LBB0_166
	global_load_dword v184, v[112:113], off offset:40 nt
.LBB0_166:
	v_lshl_add_u64 v[186:187], v[98:99], 0, s[58:59]
	global_load_dword v186, v[186:187], off nt
	v_mov_b32_e32 v185, 1.0
	s_and_b64 vcc, exec, s[4:5]
	s_waitcnt vmcnt(0)
	v_mul_f32_e32 v184, v184, v186
	ds_write_b32 v183, v184 offset:1320
	v_mov_b32_e32 v184, 1.0
	s_cbranch_vccnz .LBB0_168
	global_load_dword v184, v[112:113], off offset:48 nt
.LBB0_168:
	v_lshl_add_u64 v[186:187], v[96:97], 0, s[58:59]
	global_load_dword v186, v[186:187], off nt
	s_and_b64 vcc, exec, s[4:5]
	s_waitcnt vmcnt(0)
	v_mul_f32_e32 v184, v184, v186
	ds_write_b32 v183, v184 offset:1584
	s_cbranch_vccnz .LBB0_170
	global_load_dword v185, v[112:113], off offset:56 nt
.LBB0_170:
	v_lshl_add_u64 v[186:187], v[94:95], 0, s[58:59]
	global_load_dword v186, v[186:187], off nt
	v_mov_b32_e32 v184, 1.0
	s_and_b64 vcc, exec, s[4:5]
	s_waitcnt vmcnt(0)
	v_mul_f32_e32 v185, v185, v186
	ds_write_b32 v183, v185 offset:1848
	v_mov_b32_e32 v185, 1.0
	s_cbranch_vccnz .LBB0_172
	global_load_dword v185, v[112:113], off offset:64 nt
.LBB0_172:
	v_lshl_add_u64 v[186:187], v[92:93], 0, s[58:59]
	global_load_dword v186, v[186:187], off nt
	s_and_b64 vcc, exec, s[4:5]
	s_waitcnt vmcnt(0)
	v_mul_f32_e32 v185, v185, v186
	ds_write_b32 v183, v185 offset:2112
	s_cbranch_vccnz .LBB0_174
	global_load_dword v184, v[112:113], off offset:72 nt
.LBB0_174:
	v_lshl_add_u64 v[186:187], v[90:91], 0, s[58:59]
	global_load_dword v186, v[186:187], off nt
	v_mov_b32_e32 v185, 1.0
	s_and_b64 vcc, exec, s[4:5]
	s_waitcnt vmcnt(0)
	v_mul_f32_e32 v184, v184, v186
	ds_write_b32 v183, v184 offset:2376
	v_mov_b32_e32 v184, 1.0
	s_cbranch_vccnz .LBB0_176
	global_load_dword v184, v[112:113], off offset:80 nt
.LBB0_176:
	v_lshl_add_u64 v[186:187], v[88:89], 0, s[58:59]
	global_load_dword v186, v[186:187], off nt
	s_and_b64 vcc, exec, s[4:5]
	s_waitcnt vmcnt(0)
	v_mul_f32_e32 v184, v184, v186
	ds_write_b32 v183, v184 offset:2640
	s_cbranch_vccnz .LBB0_178
	global_load_dword v185, v[112:113], off offset:88 nt
.LBB0_178:
	v_lshl_add_u64 v[186:187], v[86:87], 0, s[58:59]
	global_load_dword v184, v[186:187], off nt
	v_mov_b32_e32 v186, 1.0
	s_and_b64 vcc, exec, s[4:5]
	s_waitcnt vmcnt(0)
	v_mul_f32_e32 v184, v185, v184
	ds_write_b32 v183, v184 offset:2904
	v_mov_b32_e32 v184, 1.0
	s_cbranch_vccnz .LBB0_180
	global_load_dword v184, v[112:113], off offset:96 nt
.LBB0_180:
	v_lshl_add_u64 v[188:189], v[84:85], 0, s[58:59]
	global_load_dword v185, v[188:189], off nt
	s_and_b64 vcc, exec, s[4:5]
	s_waitcnt vmcnt(0)
	v_mul_f32_e32 v184, v184, v185
	ds_write_b32 v183, v184 offset:3168
	s_cbranch_vccnz .LBB0_182
	global_load_dword v186, v[112:113], off offset:104 nt
.LBB0_182:
	v_lshl_add_u64 v[184:185], v[82:83], 0, s[58:59]
	global_load_dword v185, v[184:185], off nt
	v_mov_b32_e32 v184, 1.0
	s_and_b64 vcc, exec, s[4:5]
	s_waitcnt vmcnt(0)
	v_mul_f32_e32 v185, v186, v185
	ds_write_b32 v183, v185 offset:3432
	v_mov_b32_e32 v185, 1.0
	s_cbranch_vccnz .LBB0_184
	global_load_dword v185, v[112:113], off offset:112 nt
.LBB0_184:
	v_lshl_add_u64 v[186:187], v[80:81], 0, s[58:59]
	global_load_dword v186, v[186:187], off nt
	s_and_b64 vcc, exec, s[4:5]
	s_waitcnt vmcnt(0)
	v_mul_f32_e32 v185, v185, v186
	ds_write_b32 v183, v185 offset:3696
	s_cbranch_vccnz .LBB0_153
	global_load_dword v184, v[112:113], off offset:120 nt
	s_branch .LBB0_153

; __device__ __forceinline__ unsigned pk2(float lo, float hi) { return pg8::cvt_pk_bf16(lo, hi); }
; __global__ void __launch_bounds__(NTHR, 2) hybrid_fwd(Args args) {
;     ...
;         for (int row = gw; row < TM; row += NGW) {
;             const f32x4* xr = (const f32x4*)(mem + (size_t)row * DM) + lane; float s = 0.f;
;             unsigned long long* o8 = (unsigned long long*)(MEMB + (size_t)row * DM) + lane;
; #pragma unroll
;             for (int j = 0; j < 4; ++j) { const f32x4 v = xr[64 * j]; s += (v[0] * v[0] + v[1] * v[1]) + (v[2] * v[2] + v[3] * v[3]);
;                 o8[64 * j] = (unsigned long long)pk2(v[0], v[1]) | ((unsigned long long)pk2(v[2], v[3]) << 32); }
;             s = wave_sum(s); if (lane == 0) SSQM[row] = s;
;         }
.LBB0_203:
	v_lshl_add_u64 v[10:11], s[24:25], 0, v[0:1]
	v_add_co_u32_e32 v22, vcc, s15, v10
	s_waitcnt lgkmcnt(0)
	global_load_dwordx4 v[6:9], v[2:3], off offset:-2048 nt
	v_addc_co_u32_e32 v23, vcc, 0, v11, vcc
	s_waitcnt vmcnt(0)
	v_cvt_pk_bf16_f32 v10, v6, v7
	v_cvt_pk_bf16_f32 v11, v8, v9
	global_store_dwordx2 v[22:23], v[10:11], off
	global_load_dwordx4 v[10:13], v[2:3], off offset:-1024 nt
	s_waitcnt vmcnt(0)
	v_cvt_pk_bf16_f32 v14, v10, v11
	v_cvt_pk_bf16_f32 v15, v12, v13
	global_store_dwordx2 v[22:23], v[14:15], off offset:512
	global_load_dwordx4 v[14:17], v[2:3], off nt
	s_waitcnt vmcnt(0)
	v_cvt_pk_bf16_f32 v18, v14, v15
	v_cvt_pk_bf16_f32 v19, v16, v17
	global_store_dwordx2 v[22:23], v[18:19], off offset:1024
	global_load_dwordx4 v[18:21], v[2:3], off offset:1024 nt
	v_mul_f32_e32 v5, v7, v7
	v_mul_f32_e32 v7, v9, v9
	v_fmac_f32_e32 v5, v6, v6
	v_fmac_f32_e32 v7, v8, v8
	v_add_f32_e32 v5, v5, v7
	s_waitcnt vmcnt(0)
	v_cvt_pk_bf16_f32 v8, v18, v19
	v_mul_f32_e32 v6, v11, v11
	v_mul_f32_e32 v7, v13, v13
	v_fmac_f32_e32 v6, v10, v10
	v_fmac_f32_e32 v7, v12, v12
	v_add_f32_e32 v6, v6, v7
	v_add_f32_e32 v5, v5, v6
	v_mul_f32_e32 v6, v15, v15
	v_mul_f32_e32 v7, v17, v17
	v_fmac_f32_e32 v6, v14, v14
	v_fmac_f32_e32 v7, v16, v16
	v_add_f32_e32 v6, v6, v7
	v_add_f32_e32 v5, v5, v6
	v_mul_f32_e32 v6, v19, v19
	v_mul_f32_e32 v7, v21, v21
	v_fmac_f32_e32 v6, v18, v18
	v_fmac_f32_e32 v7, v20, v20
	v_add_f32_e32 v6, v6, v7
	v_add_f32_e32 v5, v5, v6
	ds_bpermute_b32 v6, v218, v5
	v_cvt_pk_bf16_f32 v9, v20, v21
	global_store_dwordx2 v[22:23], v[8:9], off offset:1536
	s_waitcnt lgkmcnt(0)
	v_add_f32_e32 v5, v5, v6
	ds_bpermute_b32 v6, v219, v5
	s_waitcnt lgkmcnt(0)
	v_add_f32_e32 v5, v5, v6
	ds_bpermute_b32 v6, v34, v5
	s_waitcnt lgkmcnt(0)
	v_add_f32_e32 v5, v5, v6
	ds_bpermute_b32 v6, v50, v5
	s_waitcnt lgkmcnt(0)
	v_add_f32_e32 v5, v5, v6
	ds_bpermute_b32 v6, v213, v5
	s_waitcnt lgkmcnt(0)
	v_add_f32_e32 v5, v5, v6
	ds_bpermute_b32 v6, v220, v5
	s_and_saveexec_b64 s[12:13], s[4:5]
	s_cbranch_execz .LBB0_202
	s_add_u32 s30, s24, s3
	s_addc_u32 s31, s25, s14
	s_waitcnt lgkmcnt(0)
	v_add_f32_e32 v5, v5, v6
	global_store_dword v4, v5, s[30:31]
	s_branch .LBB0_202
